# branch GEMM: gate loads of both segment hooks and final epilogue software-pipelined through a 6-deep register ring with counted vmcnt
# speedup vs baseline: 1.1993x; 1.0106x over previous
.LBB0_963:
	s_cmp_eq_u32 s71, 2
	s_cbranch_scc1 .LBB0_959
	s_lshl_b32 s26, s71, 12
	v_lshl_add_u64 v[248:249], v[178:179], 0, s[26:27]
	s_mov_b32 s98, 0x800
	s_mov_b32 s99, 0
	v_lshl_add_u64 v[248:249], v[248:249], 0, s[98:99]
	global_load_dwordx4 v[200:203], v[248:249], off offset:-2048
	global_load_dwordx4 v[204:207], v[248:249], off offset:2048
	global_load_dwordx4 v[208:211], v[248:249], off offset:-1792
	global_load_dwordx4 v[212:215], v[248:249], off offset:2304
	s_mov_b32 s98, 0x66000
	s_mov_b32 s99, 0
	v_lshl_add_u64 v[248:249], v[248:249], 0, s[98:99]
	global_load_dwordx4 v[216:219], v[248:249], off offset:-2048
	global_load_dwordx4 v[220:223], v[248:249], off offset:2048
	global_load_dwordx4 v[224:227], v[248:249], off offset:-1792
	global_load_dwordx4 v[228:231], v[248:249], off offset:2304
	s_mov_b32 s98, 0x66000
	s_mov_b32 s99, 0
	v_lshl_add_u64 v[248:249], v[248:249], 0, s[98:99]
	global_load_dwordx4 v[232:235], v[248:249], off offset:-2048
	global_load_dwordx4 v[236:239], v[248:249], off offset:2048
	global_load_dwordx4 v[240:243], v[248:249], off offset:-1792
	global_load_dwordx4 v[244:247], v[248:249], off offset:2304
	v_lshl_add_u64 v[132:133], v[178:179], 0, s[26:27]
	v_add_co_u32_e32 v98, vcc, 0x1000, v132
	s_nop 0
	v_addc_co_u32_e32 v99, vcc, 0, v133, vcc
	s_waitcnt vmcnt(10)
	v_mov_b32_e32 v134, v200
	v_mov_b32_e32 v135, v201
	v_mov_b32_e32 v136, v202
	v_mov_b32_e32 v137, v203
	v_mov_b32_e32 v180, v204
	v_mov_b32_e32 v181, v205
	v_mov_b32_e32 v182, v206
	v_mov_b32_e32 v183, v207
	s_mov_b32 s98, 0x66000
	s_mov_b32 s99, 0
	v_lshl_add_u64 v[248:249], v[248:249], 0, s[98:99]
	global_load_dwordx4 v[200:203], v[248:249], off offset:-2048
	global_load_dwordx4 v[204:207], v[248:249], off offset:2048
	v_lshlrev_b32_e32 v96, 16, v180
	v_mul_f32_e32 v96, 0xbfb8aa3b, v96
	v_exp_f32_e32 v138, v96
	v_lshlrev_b32_e32 v96, 16, v134
	v_mul_f32_e32 v96, 0xbfb8aa3b, v96
	v_exp_f32_e32 v96, v96
	s_nop 0
	v_add_f32_e32 v96, 1.0, v96
	v_rcp_f32_e32 v184, v96
	v_lshlrev_b32_e32 v96, 16, v182
	v_mul_f32_e32 v96, 0xbfb8aa3b, v96
	v_exp_f32_e32 v186, v96
	v_lshlrev_b32_e32 v96, 16, v136
	v_mul_f32_e32 v96, 0xbfb8aa3b, v96
	v_exp_f32_e32 v96, v96
	s_nop 0
	v_add_f32_e32 v96, 1.0, v96
	v_rcp_f32_e32 v188, v96
	v_and_b32_e32 v96, 0xffff0000, v180
	v_mul_f32_e32 v96, 0xbfb8aa3b, v96
	v_exp_f32_e32 v139, v96
	v_and_b32_e32 v96, 0xffff0000, v134
	v_mul_f32_e32 v96, 0xbfb8aa3b, v96
	v_exp_f32_e32 v96, v96
	v_pk_add_f32 v[138:139], v[138:139], 1.0 op_sel_hi:[1,0]
	v_add_f32_e32 v96, 1.0, v96
	v_rcp_f32_e32 v185, v96
	v_and_b32_e32 v96, 0xffff0000, v182
	v_mul_f32_e32 v96, 0xbfb8aa3b, v96
	v_exp_f32_e32 v187, v96
	v_and_b32_e32 v96, 0xffff0000, v136
	v_mul_f32_e32 v96, 0xbfb8aa3b, v96
	v_exp_f32_e32 v96, v96
	v_pk_mul_f32 v[138:139], v[138:139], v[184:185]
	v_add_f32_e32 v96, 1.0, v96
	v_rcp_f32_e32 v189, v96
	v_lshlrev_b32_e32 v96, 16, v181
	v_mul_f32_e32 v96, 0xbfb8aa3b, v96
	v_exp_f32_e32 v180, v96
	v_lshlrev_b32_e32 v96, 16, v135
	v_mul_f32_e32 v96, 0xbfb8aa3b, v96
	v_exp_f32_e32 v96, v96
	v_pk_mul_f32 v[128:129], v[128:129], v[138:139]
	v_pk_add_f32 v[138:139], v[186:187], 1.0 op_sel_hi:[1,0]
	v_add_f32_e32 v96, 1.0, v96
	v_rcp_f32_e32 v134, v96
	v_lshlrev_b32_e32 v96, 16, v183
	v_mul_f32_e32 v96, 0xbfb8aa3b, v96
	v_exp_f32_e32 v182, v96
	v_lshlrev_b32_e32 v96, 16, v137
	v_mul_f32_e32 v96, 0xbfb8aa3b, v96
	v_exp_f32_e32 v96, v96
	v_pk_mul_f32 v[138:139], v[138:139], v[188:189]
	v_add_f32_e32 v96, 1.0, v96
	v_rcp_f32_e32 v136, v96
	v_and_b32_e32 v96, 0xffff0000, v181
	v_mul_f32_e32 v96, 0xbfb8aa3b, v96
	v_exp_f32_e32 v181, v96
	v_and_b32_e32 v96, 0xffff0000, v135
	v_mul_f32_e32 v96, 0xbfb8aa3b, v96
	v_exp_f32_e32 v96, v96
	v_pk_add_f32 v[180:181], v[180:181], 1.0 op_sel_hi:[1,0]
	v_pk_mul_f32 v[124:125], v[124:125], v[138:139]
	v_add_f32_e32 v96, 1.0, v96
	v_rcp_f32_e32 v135, v96
	v_and_b32_e32 v96, 0xffff0000, v183
	v_mul_f32_e32 v96, 0xbfb8aa3b, v96
	v_exp_f32_e32 v183, v96
	v_and_b32_e32 v96, 0xffff0000, v137
	v_mul_f32_e32 v96, 0xbfb8aa3b, v96
	v_exp_f32_e32 v96, v96
	v_pk_mul_f32 v[134:135], v[180:181], v[134:135]
	v_add_f32_e32 v96, 1.0, v96
	v_rcp_f32_e32 v137, v96
	v_pk_mul_f32 v[130:131], v[130:131], v[134:135]
	v_pk_add_f32 v[134:135], v[182:183], 1.0 op_sel_hi:[1,0]
	s_nop 0
	v_pk_mul_f32 v[134:135], v[134:135], v[136:137]
	s_nop 0
	v_pk_mul_f32 v[126:127], v[126:127], v[134:135]
	s_nop 0
	s_waitcnt vmcnt(10)
	v_mov_b32_e32 v132, v208
	v_mov_b32_e32 v133, v209
	v_mov_b32_e32 v134, v210
	v_mov_b32_e32 v135, v211
	v_mov_b32_e32 v136, v212
	v_mov_b32_e32 v137, v213
	v_mov_b32_e32 v138, v214
	v_mov_b32_e32 v139, v215
	global_load_dwordx4 v[208:211], v[248:249], off offset:-1792
	global_load_dwordx4 v[212:215], v[248:249], off offset:2304
	v_lshlrev_b32_e32 v96, 16, v136
	v_mul_f32_e32 v96, 0xbfb8aa3b, v96
	v_exp_f32_e32 v98, v96
	v_lshlrev_b32_e32 v96, 16, v132
	v_mul_f32_e32 v96, 0xbfb8aa3b, v96
	v_exp_f32_e32 v96, v96
	s_nop 0
	v_add_f32_e32 v96, 1.0, v96
	v_rcp_f32_e32 v180, v96
	v_lshlrev_b32_e32 v96, 16, v138
	v_mul_f32_e32 v96, 0xbfb8aa3b, v96
	v_exp_f32_e32 v182, v96
	v_lshlrev_b32_e32 v96, 16, v134
	v_mul_f32_e32 v96, 0xbfb8aa3b, v96
	v_exp_f32_e32 v96, v96
	s_nop 0
	v_add_f32_e32 v96, 1.0, v96
	v_rcp_f32_e32 v184, v96
	v_and_b32_e32 v96, 0xffff0000, v136
	v_mul_f32_e32 v96, 0xbfb8aa3b, v96
	v_exp_f32_e32 v99, v96
	v_and_b32_e32 v96, 0xffff0000, v132
	v_mul_f32_e32 v96, 0xbfb8aa3b, v96
	v_exp_f32_e32 v96, v96
	v_pk_add_f32 v[98:99], v[98:99], 1.0 op_sel_hi:[1,0]
	v_add_f32_e32 v96, 1.0, v96
	v_rcp_f32_e32 v181, v96
	v_and_b32_e32 v96, 0xffff0000, v138
	v_mul_f32_e32 v96, 0xbfb8aa3b, v96
	v_exp_f32_e32 v183, v96
	v_and_b32_e32 v96, 0xffff0000, v134
	v_mul_f32_e32 v96, 0xbfb8aa3b, v96
	v_exp_f32_e32 v96, v96
	v_pk_mul_f32 v[98:99], v[98:99], v[180:181]
	v_lshlrev_b64 v[180:181], 1, v[174:175]
	v_pk_mul_f32 v[120:121], v[120:121], v[98:99]
	v_add_f32_e32 v96, 1.0, v96
	v_rcp_f32_e32 v185, v96
	v_lshlrev_b32_e32 v96, 16, v137
	v_mul_f32_e32 v96, 0xbfb8aa3b, v96
	v_exp_f32_e32 v136, v96
	v_lshlrev_b32_e32 v96, 16, v133
	v_mul_f32_e32 v96, 0xbfb8aa3b, v96
	v_exp_f32_e32 v96, v96
	s_nop 0
	v_add_f32_e32 v96, 1.0, v96
	v_rcp_f32_e32 v132, v96
	v_lshlrev_b32_e32 v96, 16, v139
	v_mul_f32_e32 v96, 0xbfb8aa3b, v96
	v_exp_f32_e32 v138, v96
	v_lshlrev_b32_e32 v96, 16, v135
	v_mul_f32_e32 v96, 0xbfb8aa3b, v96
	v_exp_f32_e32 v96, v96
	s_nop 0
	v_add_f32_e32 v96, 1.0, v96
	v_rcp_f32_e32 v134, v96
	v_and_b32_e32 v96, 0xffff0000, v137
	v_mul_f32_e32 v96, 0xbfb8aa3b, v96
	v_exp_f32_e32 v137, v96
	v_and_b32_e32 v96, 0xffff0000, v133
	v_mul_f32_e32 v96, 0xbfb8aa3b, v96
	v_exp_f32_e32 v96, v96
	v_pk_add_f32 v[136:137], v[136:137], 1.0 op_sel_hi:[1,0]
	v_add_f32_e32 v96, 1.0, v96
	v_rcp_f32_e32 v133, v96
	v_and_b32_e32 v96, 0xffff0000, v139
	v_mul_f32_e32 v96, 0xbfb8aa3b, v96
	v_exp_f32_e32 v139, v96
	v_and_b32_e32 v96, 0xffff0000, v135
	v_mul_f32_e32 v96, 0xbfb8aa3b, v96
	v_exp_f32_e32 v96, v96
	v_pk_mul_f32 v[132:133], v[136:137], v[132:133]
	v_pk_add_f32 v[98:99], v[138:139], 1.0 op_sel_hi:[1,0]
	v_pk_mul_f32 v[122:123], v[122:123], v[132:133]
	v_add_f32_e32 v96, 1.0, v96
	v_rcp_f32_e32 v135, v96
	v_pk_add_f32 v[132:133], v[182:183], 1.0 op_sel_hi:[1,0]
	v_mov_b32_e32 v96, 0
	v_pk_mul_f32 v[132:133], v[132:133], v[184:185]
	v_pk_mul_f32 v[98:99], v[98:99], v[134:135]
	v_pk_mul_f32 v[116:117], v[116:117], v[132:133]
	v_pk_mul_f32 v[118:119], v[118:119], v[98:99]
	v_mov_b64_e32 v[98:99], s[34:35]
	s_nop 0
	v_add_u32_e32 v132, v96, v170
	v_mad_i64_i32 v[132:133], s[12:13], v132, s40, v[98:99]
	v_lshl_add_u64 v[132:133], v[132:133], 0, s[26:27]
	v_lshl_add_u64 v[132:133], v[132:133], 0, v[180:181]
	v_add_co_u32_e32 v136, vcc, s20, v132
	s_nop 1
	v_addc_co_u32_e32 v137, vcc, 0, v133, vcc
	s_waitcnt vmcnt(10)
	v_mov_b32_e32 v182, v216
	v_mov_b32_e32 v183, v217
	v_mov_b32_e32 v184, v218
	v_mov_b32_e32 v185, v219
	v_mov_b32_e32 v186, v220
	v_mov_b32_e32 v187, v221
	v_mov_b32_e32 v188, v222
	v_mov_b32_e32 v189, v223
	s_mov_b32 s98, 0x1fe000
	s_mov_b32 s99, 0
	v_lshl_add_u64 v[248:249], v[248:249], 0, s[98:99]
	global_load_dwordx4 v[216:219], v[248:249], off offset:-2048
	global_load_dwordx4 v[220:223], v[248:249], off offset:2048
	v_lshlrev_b32_e32 v135, 16, v182
	v_mul_f32_e32 v135, 0xbfb8aa3b, v135
	v_exp_f32_e32 v135, v135
	v_and_b32_e32 v139, 0xffff0000, v182
	v_mul_f32_e32 v139, 0xbfb8aa3b, v139
	v_exp_f32_e32 v139, v139
	v_and_b32_e32 v149, 0xffff0000, v188
	v_add_f32_e32 v135, 1.0, v135
	v_mul_f32_e32 v149, 0xbfb8aa3b, v149
	v_rcp_f32_e32 v138, v135
	v_lshlrev_b32_e32 v135, 16, v188
	v_exp_f32_e32 v197, v149
	v_and_b32_e32 v149, 0xffff0000, v184
	v_mul_f32_e32 v135, 0xbfb8aa3b, v135
	v_mul_f32_e32 v149, 0xbfb8aa3b, v149
	v_exp_f32_e32 v196, v135
	v_lshlrev_b32_e32 v135, 16, v184
	v_exp_f32_e32 v149, v149
	v_mul_f32_e32 v135, 0xbfb8aa3b, v135
	v_exp_f32_e32 v135, v135
	v_lshlrev_b32_e32 v134, 16, v186
	v_add_f32_e32 v149, 1.0, v149
	v_rcp_f32_e32 v199, v149
	v_lshlrev_b32_e32 v149, 16, v187
	v_add_f32_e32 v135, 1.0, v135
	v_mul_f32_e32 v149, 0xbfb8aa3b, v149
	v_rcp_f32_e32 v198, v135
	v_and_b32_e32 v135, 0xffff0000, v186
	v_exp_f32_e32 v186, v149
	v_lshlrev_b32_e32 v149, 16, v183
	v_mul_f32_e32 v149, 0xbfb8aa3b, v149
	v_exp_f32_e32 v149, v149
	v_mul_f32_e32 v134, 0xbfb8aa3b, v134
	v_mul_f32_e32 v135, 0xbfb8aa3b, v135
	v_exp_f32_e32 v134, v134
	v_add_f32_e32 v149, 1.0, v149
	v_rcp_f32_e32 v182, v149
	v_lshlrev_b32_e32 v149, 16, v189
	v_mul_f32_e32 v149, 0xbfb8aa3b, v149
	v_exp_f32_e32 v188, v149
	v_lshlrev_b32_e32 v149, 16, v185
	v_mul_f32_e32 v149, 0xbfb8aa3b, v149
	v_exp_f32_e32 v149, v149
	v_exp_f32_e32 v135, v135
	v_add_f32_e32 v139, 1.0, v139
	v_rcp_f32_e32 v139, v139
	v_add_f32_e32 v149, 1.0, v149
	v_rcp_f32_e32 v184, v149
	v_and_b32_e32 v149, 0xffff0000, v187
	v_pk_add_f32 v[134:135], v[134:135], 1.0 op_sel_hi:[1,0]
	v_mul_f32_e32 v149, 0xbfb8aa3b, v149
	v_pk_mul_f32 v[134:135], v[134:135], v[138:139]
	v_exp_f32_e32 v187, v149
	v_and_b32_e32 v149, 0xffff0000, v183
	v_pk_mul_f32 v[112:113], v[112:113], v[134:135]
	v_and_b32_e32 v134, 0xffff0000, v189
	v_mul_f32_e32 v149, 0xbfb8aa3b, v149
	v_mul_f32_e32 v134, 0xbfb8aa3b, v134
	v_exp_f32_e32 v149, v149
	v_exp_f32_e32 v189, v134
	v_and_b32_e32 v134, 0xffff0000, v185
	v_mul_f32_e32 v134, 0xbfb8aa3b, v134
	v_exp_f32_e32 v134, v134
	v_add_f32_e32 v149, 1.0, v149
	v_rcp_f32_e32 v183, v149
	v_pk_add_f32 v[186:187], v[186:187], 1.0 op_sel_hi:[1,0]
	v_add_f32_e32 v134, 1.0, v134
	v_rcp_f32_e32 v185, v134
	v_pk_mul_f32 v[138:139], v[186:187], v[182:183]
	v_pk_add_f32 v[134:135], v[188:189], 1.0 op_sel_hi:[1,0]
	v_pk_mul_f32 v[114:115], v[114:115], v[138:139]
	v_pk_add_f32 v[138:139], v[196:197], 1.0 op_sel_hi:[1,0]
	v_pk_mul_f32 v[134:135], v[134:135], v[184:185]
	v_pk_mul_f32 v[138:139], v[138:139], v[198:199]
	v_pk_mul_f32 v[110:111], v[110:111], v[134:135]
	v_pk_mul_f32 v[108:109], v[108:109], v[138:139]
	s_nop 0
	s_waitcnt vmcnt(10)
	v_mov_b32_e32 v132, v224
	v_mov_b32_e32 v133, v225
	v_mov_b32_e32 v134, v226
	v_mov_b32_e32 v135, v227
	v_mov_b32_e32 v136, v228
	v_mov_b32_e32 v137, v229
	v_mov_b32_e32 v138, v230
	v_mov_b32_e32 v139, v231
	global_load_dwordx4 v[224:227], v[248:249], off offset:-1792
	global_load_dwordx4 v[228:231], v[248:249], off offset:2304
	v_lshlrev_b32_e32 v149, 16, v136
	v_mul_f32_e32 v149, 0xbfb8aa3b, v149
	v_exp_f32_e32 v184, v149
	v_lshlrev_b32_e32 v149, 16, v132
	v_and_b32_e32 v132, 0xffff0000, v132
	v_mul_f32_e32 v132, 0xbfb8aa3b, v132
	v_exp_f32_e32 v132, v132
	v_and_b32_e32 v136, 0xffff0000, v136
	v_mul_f32_e32 v136, 0xbfb8aa3b, v136
	v_exp_f32_e32 v185, v136
	v_add_f32_e32 v132, 1.0, v132
	v_rcp_f32_e32 v187, v132
	v_and_b32_e32 v132, 0xffff0000, v138
	v_mul_f32_e32 v132, 0xbfb8aa3b, v132
	v_exp_f32_e32 v183, v132
	v_and_b32_e32 v132, 0xffff0000, v134
	v_mul_f32_e32 v132, 0xbfb8aa3b, v132
	v_exp_f32_e32 v132, v132
	v_mul_f32_e32 v149, 0xbfb8aa3b, v149
	v_exp_f32_e32 v149, v149
	v_pk_add_f32 v[184:185], v[184:185], 1.0 op_sel_hi:[1,0]
	v_add_f32_e32 v132, 1.0, v132
	v_rcp_f32_e32 v189, v132
	v_lshlrev_b32_e32 v132, 16, v137
	v_mul_f32_e32 v132, 0xbfb8aa3b, v132
	v_exp_f32_e32 v136, v132
	v_lshlrev_b32_e32 v132, 16, v133
	v_and_b32_e32 v133, 0xffff0000, v133
	v_mul_f32_e32 v132, 0xbfb8aa3b, v132
	v_mul_f32_e32 v133, 0xbfb8aa3b, v133
	v_exp_f32_e32 v132, v132
	v_exp_f32_e32 v133, v133
	v_and_b32_e32 v137, 0xffff0000, v137
	v_mul_f32_e32 v137, 0xbfb8aa3b, v137
	v_add_f32_e32 v132, 1.0, v132
	v_exp_f32_e32 v137, v137
	v_add_f32_e32 v133, 1.0, v133
	v_rcp_f32_e32 v132, v132
	v_rcp_f32_e32 v133, v133
	v_add_f32_e32 v149, 1.0, v149
	v_rcp_f32_e32 v186, v149
	v_lshlrev_b32_e32 v149, 16, v138
	v_pk_add_f32 v[136:137], v[136:137], 1.0 op_sel_hi:[1,0]
	v_mul_f32_e32 v149, 0xbfb8aa3b, v149
	v_pk_mul_f32 v[132:133], v[136:137], v[132:133]
	v_exp_f32_e32 v182, v149
	v_lshlrev_b32_e32 v149, 16, v134
	v_lshlrev_b32_e32 v134, 16, v139
	v_pk_mul_f32 v[106:107], v[106:107], v[132:133]
	v_and_b32_e32 v132, 0xffff0000, v139
	v_mul_f32_e32 v134, 0xbfb8aa3b, v134
	v_mul_f32_e32 v132, 0xbfb8aa3b, v132
	v_exp_f32_e32 v138, v134
	v_lshlrev_b32_e32 v134, 16, v135
	v_exp_f32_e32 v139, v132
	v_and_b32_e32 v132, 0xffff0000, v135
	v_mul_f32_e32 v149, 0xbfb8aa3b, v149
	v_mul_f32_e32 v134, 0xbfb8aa3b, v134
	v_mul_f32_e32 v132, 0xbfb8aa3b, v132
	v_exp_f32_e32 v149, v149
	v_exp_f32_e32 v134, v134
	v_exp_f32_e32 v132, v132
	v_pk_add_f32 v[136:137], v[182:183], 1.0 op_sel_hi:[1,0]
	v_add_f32_e32 v149, 1.0, v149
	v_add_f32_e32 v134, 1.0, v134
	v_add_f32_e32 v132, 1.0, v132
	v_rcp_f32_e32 v188, v149
	v_rcp_f32_e32 v134, v134
	v_rcp_f32_e32 v135, v132
	v_pk_add_f32 v[132:133], v[138:139], 1.0 op_sel_hi:[1,0]
	v_pk_mul_f32 v[136:137], v[136:137], v[188:189]
	v_pk_mul_f32 v[184:185], v[184:185], v[186:187]
	v_pk_mul_f32 v[132:133], v[132:133], v[134:135]
	v_pk_mul_f32 v[100:101], v[100:101], v[136:137]
	v_pk_mul_f32 v[102:103], v[102:103], v[132:133]
	v_pk_mul_f32 v[104:105], v[104:105], v[184:185]
	s_nop 0
	v_add_u32_e32 v132, v96, v168
	v_mad_i64_i32 v[132:133], s[12:13], v132, s40, v[98:99]
	v_lshl_add_u64 v[132:133], v[132:133], 0, s[26:27]
	v_lshl_add_u64 v[132:133], v[132:133], 0, v[180:181]
	v_add_co_u32_e32 v136, vcc, s20, v132
	s_nop 1
	v_addc_co_u32_e32 v137, vcc, 0, v133, vcc
	s_waitcnt vmcnt(10)
	v_mov_b32_e32 v182, v232
	v_mov_b32_e32 v183, v233
	v_mov_b32_e32 v184, v234
	v_mov_b32_e32 v185, v235
	v_mov_b32_e32 v186, v236
	v_mov_b32_e32 v187, v237
	v_mov_b32_e32 v188, v238
	v_mov_b32_e32 v189, v239
	s_mov_b32 s98, 0x66000
	s_mov_b32 s99, 0
	v_lshl_add_u64 v[248:249], v[248:249], 0, s[98:99]
	global_load_dwordx4 v[232:235], v[248:249], off offset:-2048
	global_load_dwordx4 v[236:239], v[248:249], off offset:2048
	v_lshlrev_b32_e32 v135, 16, v182
	v_mul_f32_e32 v135, 0xbfb8aa3b, v135
	v_exp_f32_e32 v135, v135
	v_and_b32_e32 v139, 0xffff0000, v182
	v_mul_f32_e32 v139, 0xbfb8aa3b, v139
	v_exp_f32_e32 v139, v139
	v_and_b32_e32 v149, 0xffff0000, v188
	v_add_f32_e32 v135, 1.0, v135
	v_mul_f32_e32 v149, 0xbfb8aa3b, v149
	v_rcp_f32_e32 v138, v135
	v_lshlrev_b32_e32 v135, 16, v188
	v_exp_f32_e32 v197, v149
	v_and_b32_e32 v149, 0xffff0000, v184
	v_mul_f32_e32 v135, 0xbfb8aa3b, v135
	v_mul_f32_e32 v149, 0xbfb8aa3b, v149
	v_exp_f32_e32 v196, v135
	v_lshlrev_b32_e32 v135, 16, v184
	v_exp_f32_e32 v149, v149
	v_mul_f32_e32 v135, 0xbfb8aa3b, v135
	v_exp_f32_e32 v135, v135
	v_lshlrev_b32_e32 v134, 16, v186
	v_add_f32_e32 v149, 1.0, v149
	v_rcp_f32_e32 v199, v149
	v_lshlrev_b32_e32 v149, 16, v187
	v_add_f32_e32 v135, 1.0, v135
	v_mul_f32_e32 v149, 0xbfb8aa3b, v149
	v_rcp_f32_e32 v198, v135
	v_and_b32_e32 v135, 0xffff0000, v186
	v_exp_f32_e32 v186, v149
	v_lshlrev_b32_e32 v149, 16, v183
	v_mul_f32_e32 v149, 0xbfb8aa3b, v149
	v_exp_f32_e32 v149, v149
	v_mul_f32_e32 v134, 0xbfb8aa3b, v134
	v_mul_f32_e32 v135, 0xbfb8aa3b, v135
	v_exp_f32_e32 v134, v134
	v_add_f32_e32 v149, 1.0, v149
	v_rcp_f32_e32 v182, v149
	v_lshlrev_b32_e32 v149, 16, v189
	v_mul_f32_e32 v149, 0xbfb8aa3b, v149
	v_exp_f32_e32 v188, v149
	v_lshlrev_b32_e32 v149, 16, v185
	v_mul_f32_e32 v149, 0xbfb8aa3b, v149
	v_exp_f32_e32 v149, v149
	v_exp_f32_e32 v135, v135
	v_add_f32_e32 v139, 1.0, v139
	v_rcp_f32_e32 v139, v139
	v_add_f32_e32 v149, 1.0, v149
	v_rcp_f32_e32 v184, v149
	v_and_b32_e32 v149, 0xffff0000, v187
	v_pk_add_f32 v[134:135], v[134:135], 1.0 op_sel_hi:[1,0]
	v_mul_f32_e32 v149, 0xbfb8aa3b, v149
	v_pk_mul_f32 v[134:135], v[134:135], v[138:139]
	v_exp_f32_e32 v187, v149
	v_and_b32_e32 v149, 0xffff0000, v183
	v_pk_mul_f32 v[92:93], v[92:93], v[134:135]
	v_and_b32_e32 v134, 0xffff0000, v189
	v_mul_f32_e32 v149, 0xbfb8aa3b, v149
	v_mul_f32_e32 v134, 0xbfb8aa3b, v134
	v_exp_f32_e32 v149, v149
	v_exp_f32_e32 v189, v134
	v_and_b32_e32 v134, 0xffff0000, v185
	v_mul_f32_e32 v134, 0xbfb8aa3b, v134
	v_exp_f32_e32 v134, v134
	v_add_f32_e32 v149, 1.0, v149
	v_rcp_f32_e32 v183, v149
	v_pk_add_f32 v[186:187], v[186:187], 1.0 op_sel_hi:[1,0]
	v_add_f32_e32 v134, 1.0, v134
	v_rcp_f32_e32 v185, v134
	v_pk_mul_f32 v[138:139], v[186:187], v[182:183]
	v_pk_add_f32 v[134:135], v[188:189], 1.0 op_sel_hi:[1,0]
	v_pk_mul_f32 v[94:95], v[94:95], v[138:139]
	v_pk_add_f32 v[138:139], v[196:197], 1.0 op_sel_hi:[1,0]
	v_pk_mul_f32 v[134:135], v[134:135], v[184:185]
	v_pk_mul_f32 v[138:139], v[138:139], v[198:199]
	v_pk_mul_f32 v[90:91], v[90:91], v[134:135]
	v_pk_mul_f32 v[88:89], v[88:89], v[138:139]
	s_nop 0
	s_waitcnt vmcnt(10)
	v_mov_b32_e32 v132, v240
	v_mov_b32_e32 v133, v241
	v_mov_b32_e32 v134, v242
	v_mov_b32_e32 v135, v243
	v_mov_b32_e32 v136, v244
	v_mov_b32_e32 v137, v245
	v_mov_b32_e32 v138, v246
	v_mov_b32_e32 v139, v247
	global_load_dwordx4 v[240:243], v[248:249], off offset:-1792
	global_load_dwordx4 v[244:247], v[248:249], off offset:2304
	v_lshlrev_b32_e32 v149, 16, v136
	v_mul_f32_e32 v149, 0xbfb8aa3b, v149
	v_exp_f32_e32 v184, v149
	v_lshlrev_b32_e32 v149, 16, v132
	v_and_b32_e32 v132, 0xffff0000, v132
	v_mul_f32_e32 v132, 0xbfb8aa3b, v132
	v_exp_f32_e32 v132, v132
	v_and_b32_e32 v136, 0xffff0000, v136
	v_mul_f32_e32 v136, 0xbfb8aa3b, v136
	v_exp_f32_e32 v185, v136
	v_add_f32_e32 v132, 1.0, v132
	v_rcp_f32_e32 v187, v132
	v_and_b32_e32 v132, 0xffff0000, v138
	v_mul_f32_e32 v132, 0xbfb8aa3b, v132
	v_exp_f32_e32 v183, v132
	v_and_b32_e32 v132, 0xffff0000, v134
	v_mul_f32_e32 v132, 0xbfb8aa3b, v132
	v_exp_f32_e32 v132, v132
	v_mul_f32_e32 v149, 0xbfb8aa3b, v149
	v_exp_f32_e32 v149, v149
	v_pk_add_f32 v[184:185], v[184:185], 1.0 op_sel_hi:[1,0]
	v_add_f32_e32 v132, 1.0, v132
	v_rcp_f32_e32 v189, v132
	v_lshlrev_b32_e32 v132, 16, v137
	v_mul_f32_e32 v132, 0xbfb8aa3b, v132
	v_exp_f32_e32 v136, v132
	v_lshlrev_b32_e32 v132, 16, v133
	v_and_b32_e32 v133, 0xffff0000, v133
	v_mul_f32_e32 v132, 0xbfb8aa3b, v132
	v_mul_f32_e32 v133, 0xbfb8aa3b, v133
	v_exp_f32_e32 v132, v132
	v_exp_f32_e32 v133, v133
	v_and_b32_e32 v137, 0xffff0000, v137
	v_mul_f32_e32 v137, 0xbfb8aa3b, v137
	v_add_f32_e32 v132, 1.0, v132
	v_exp_f32_e32 v137, v137
	v_add_f32_e32 v133, 1.0, v133
	v_rcp_f32_e32 v132, v132
	v_rcp_f32_e32 v133, v133
	v_add_f32_e32 v149, 1.0, v149
	v_rcp_f32_e32 v186, v149
	v_lshlrev_b32_e32 v149, 16, v138
	v_pk_add_f32 v[136:137], v[136:137], 1.0 op_sel_hi:[1,0]
	v_mul_f32_e32 v149, 0xbfb8aa3b, v149
	v_pk_mul_f32 v[132:133], v[136:137], v[132:133]
	v_exp_f32_e32 v182, v149
	v_lshlrev_b32_e32 v149, 16, v134
	v_lshlrev_b32_e32 v134, 16, v139
	v_pk_mul_f32 v[86:87], v[86:87], v[132:133]
	v_and_b32_e32 v132, 0xffff0000, v139
	v_mul_f32_e32 v134, 0xbfb8aa3b, v134
	v_mul_f32_e32 v132, 0xbfb8aa3b, v132
	v_exp_f32_e32 v138, v134
	v_lshlrev_b32_e32 v134, 16, v135
	v_exp_f32_e32 v139, v132
	v_and_b32_e32 v132, 0xffff0000, v135
	v_mul_f32_e32 v149, 0xbfb8aa3b, v149
	v_mul_f32_e32 v134, 0xbfb8aa3b, v134
	v_mul_f32_e32 v132, 0xbfb8aa3b, v132
	v_exp_f32_e32 v149, v149
	v_exp_f32_e32 v134, v134
	v_exp_f32_e32 v132, v132
	v_pk_add_f32 v[136:137], v[182:183], 1.0 op_sel_hi:[1,0]
	v_add_f32_e32 v149, 1.0, v149
	v_add_f32_e32 v134, 1.0, v134
	v_add_f32_e32 v132, 1.0, v132
	v_rcp_f32_e32 v188, v149
	v_rcp_f32_e32 v134, v134
	v_rcp_f32_e32 v135, v132
	v_pk_add_f32 v[132:133], v[138:139], 1.0 op_sel_hi:[1,0]
	v_pk_mul_f32 v[136:137], v[136:137], v[188:189]
	v_pk_mul_f32 v[184:185], v[184:185], v[186:187]
	v_pk_mul_f32 v[132:133], v[132:133], v[134:135]
	v_pk_mul_f32 v[80:81], v[80:81], v[136:137]
	v_pk_mul_f32 v[82:83], v[82:83], v[132:133]
	v_pk_mul_f32 v[84:85], v[84:85], v[184:185]
	s_nop 0
	v_add_u32_e32 v132, v96, v156
	v_mad_i64_i32 v[132:133], s[12:13], v132, s40, v[98:99]
	v_lshl_add_u64 v[132:133], v[132:133], 0, s[26:27]
	v_lshl_add_u64 v[132:133], v[132:133], 0, v[180:181]
	v_add_co_u32_e32 v136, vcc, s20, v132
	s_nop 1
	v_addc_co_u32_e32 v137, vcc, 0, v133, vcc
	s_waitcnt vmcnt(10)
	v_mov_b32_e32 v182, v200
	v_mov_b32_e32 v183, v201
	v_mov_b32_e32 v184, v202
	v_mov_b32_e32 v185, v203
	v_mov_b32_e32 v186, v204
	v_mov_b32_e32 v187, v205
	v_mov_b32_e32 v188, v206
	v_mov_b32_e32 v189, v207
	s_mov_b32 s98, 0x66000
	s_mov_b32 s99, 0
	v_lshl_add_u64 v[248:249], v[248:249], 0, s[98:99]
	global_load_dwordx4 v[200:203], v[248:249], off offset:-2048
	global_load_dwordx4 v[204:207], v[248:249], off offset:2048
	v_lshlrev_b32_e32 v135, 16, v182
	v_mul_f32_e32 v135, 0xbfb8aa3b, v135
	v_exp_f32_e32 v135, v135
	v_and_b32_e32 v139, 0xffff0000, v182
	v_mul_f32_e32 v139, 0xbfb8aa3b, v139
	v_exp_f32_e32 v139, v139
	v_and_b32_e32 v149, 0xffff0000, v188
	v_add_f32_e32 v135, 1.0, v135
	v_mul_f32_e32 v149, 0xbfb8aa3b, v149
	v_rcp_f32_e32 v138, v135
	v_lshlrev_b32_e32 v135, 16, v188
	v_exp_f32_e32 v197, v149
	v_and_b32_e32 v149, 0xffff0000, v184
	v_mul_f32_e32 v135, 0xbfb8aa3b, v135
	v_mul_f32_e32 v149, 0xbfb8aa3b, v149
	v_exp_f32_e32 v196, v135
	v_lshlrev_b32_e32 v135, 16, v184
	v_exp_f32_e32 v149, v149
	v_mul_f32_e32 v135, 0xbfb8aa3b, v135
	v_exp_f32_e32 v135, v135
	v_lshlrev_b32_e32 v134, 16, v186
	v_add_f32_e32 v149, 1.0, v149
	v_rcp_f32_e32 v199, v149
	v_lshlrev_b32_e32 v149, 16, v187
	v_add_f32_e32 v135, 1.0, v135
	v_mul_f32_e32 v149, 0xbfb8aa3b, v149
	v_rcp_f32_e32 v198, v135
	v_and_b32_e32 v135, 0xffff0000, v186
	v_exp_f32_e32 v186, v149
	v_lshlrev_b32_e32 v149, 16, v183
	v_mul_f32_e32 v149, 0xbfb8aa3b, v149
	v_exp_f32_e32 v149, v149
	v_mul_f32_e32 v134, 0xbfb8aa3b, v134
	v_mul_f32_e32 v135, 0xbfb8aa3b, v135
	v_exp_f32_e32 v134, v134
	v_add_f32_e32 v149, 1.0, v149
	v_rcp_f32_e32 v182, v149
	v_lshlrev_b32_e32 v149, 16, v189
	v_mul_f32_e32 v149, 0xbfb8aa3b, v149
	v_exp_f32_e32 v188, v149
	v_lshlrev_b32_e32 v149, 16, v185
	v_mul_f32_e32 v149, 0xbfb8aa3b, v149
	v_exp_f32_e32 v149, v149
	v_exp_f32_e32 v135, v135
	v_add_f32_e32 v139, 1.0, v139
	v_rcp_f32_e32 v139, v139
	v_add_f32_e32 v149, 1.0, v149
	v_rcp_f32_e32 v184, v149
	v_and_b32_e32 v149, 0xffff0000, v187
	v_pk_add_f32 v[134:135], v[134:135], 1.0 op_sel_hi:[1,0]
	v_mul_f32_e32 v149, 0xbfb8aa3b, v149
	v_pk_mul_f32 v[134:135], v[134:135], v[138:139]
	v_exp_f32_e32 v187, v149
	v_and_b32_e32 v149, 0xffff0000, v183
	v_pk_mul_f32 v[76:77], v[76:77], v[134:135]
	v_and_b32_e32 v134, 0xffff0000, v189
	v_mul_f32_e32 v149, 0xbfb8aa3b, v149
	v_mul_f32_e32 v134, 0xbfb8aa3b, v134
	v_exp_f32_e32 v149, v149
	v_exp_f32_e32 v189, v134
	v_and_b32_e32 v134, 0xffff0000, v185
	v_mul_f32_e32 v134, 0xbfb8aa3b, v134
	v_exp_f32_e32 v134, v134
	v_add_f32_e32 v149, 1.0, v149
	v_rcp_f32_e32 v183, v149
	v_pk_add_f32 v[186:187], v[186:187], 1.0 op_sel_hi:[1,0]
	v_add_f32_e32 v134, 1.0, v134
	v_rcp_f32_e32 v185, v134
	v_pk_mul_f32 v[138:139], v[186:187], v[182:183]
	v_pk_add_f32 v[134:135], v[188:189], 1.0 op_sel_hi:[1,0]
	v_pk_mul_f32 v[78:79], v[78:79], v[138:139]
	v_pk_add_f32 v[138:139], v[196:197], 1.0 op_sel_hi:[1,0]
	v_pk_mul_f32 v[134:135], v[134:135], v[184:185]
	v_pk_mul_f32 v[138:139], v[138:139], v[198:199]
	v_pk_mul_f32 v[74:75], v[74:75], v[134:135]
	v_pk_mul_f32 v[72:73], v[72:73], v[138:139]
	s_nop 0
	s_waitcnt vmcnt(10)
	v_mov_b32_e32 v132, v208
	v_mov_b32_e32 v133, v209
	v_mov_b32_e32 v134, v210
	v_mov_b32_e32 v135, v211
	v_mov_b32_e32 v136, v212
	v_mov_b32_e32 v137, v213
	v_mov_b32_e32 v138, v214
	v_mov_b32_e32 v139, v215
	global_load_dwordx4 v[208:211], v[248:249], off offset:-1792
	global_load_dwordx4 v[212:215], v[248:249], off offset:2304
	v_lshlrev_b32_e32 v149, 16, v136
	v_mul_f32_e32 v149, 0xbfb8aa3b, v149
	v_exp_f32_e32 v184, v149
	v_lshlrev_b32_e32 v149, 16, v132
	v_and_b32_e32 v132, 0xffff0000, v132
	v_mul_f32_e32 v132, 0xbfb8aa3b, v132
	v_exp_f32_e32 v132, v132
	v_and_b32_e32 v136, 0xffff0000, v136
	v_mul_f32_e32 v136, 0xbfb8aa3b, v136
	v_exp_f32_e32 v185, v136
	v_add_f32_e32 v132, 1.0, v132
	v_rcp_f32_e32 v187, v132
	v_and_b32_e32 v132, 0xffff0000, v138
	v_mul_f32_e32 v132, 0xbfb8aa3b, v132
	v_exp_f32_e32 v183, v132
	v_and_b32_e32 v132, 0xffff0000, v134
	v_mul_f32_e32 v132, 0xbfb8aa3b, v132
	v_exp_f32_e32 v132, v132
	v_mul_f32_e32 v149, 0xbfb8aa3b, v149
	v_exp_f32_e32 v149, v149
	v_pk_add_f32 v[184:185], v[184:185], 1.0 op_sel_hi:[1,0]
	v_add_f32_e32 v132, 1.0, v132
	v_rcp_f32_e32 v189, v132
	v_lshlrev_b32_e32 v132, 16, v137
	v_mul_f32_e32 v132, 0xbfb8aa3b, v132
	v_exp_f32_e32 v136, v132
	v_lshlrev_b32_e32 v132, 16, v133
	v_and_b32_e32 v133, 0xffff0000, v133
	v_mul_f32_e32 v132, 0xbfb8aa3b, v132
	v_mul_f32_e32 v133, 0xbfb8aa3b, v133
	v_exp_f32_e32 v132, v132
	v_exp_f32_e32 v133, v133
	v_and_b32_e32 v137, 0xffff0000, v137
	v_mul_f32_e32 v137, 0xbfb8aa3b, v137
	v_add_f32_e32 v132, 1.0, v132
	v_exp_f32_e32 v137, v137
	v_add_f32_e32 v133, 1.0, v133
	v_rcp_f32_e32 v132, v132
	v_rcp_f32_e32 v133, v133
	v_add_f32_e32 v149, 1.0, v149
	v_rcp_f32_e32 v186, v149
	v_lshlrev_b32_e32 v149, 16, v138
	v_pk_add_f32 v[136:137], v[136:137], 1.0 op_sel_hi:[1,0]
	v_mul_f32_e32 v149, 0xbfb8aa3b, v149
	v_pk_mul_f32 v[132:133], v[136:137], v[132:133]
	v_exp_f32_e32 v182, v149
	v_lshlrev_b32_e32 v149, 16, v134
	v_lshlrev_b32_e32 v134, 16, v139
	v_pk_mul_f32 v[70:71], v[70:71], v[132:133]
	v_and_b32_e32 v132, 0xffff0000, v139
	v_mul_f32_e32 v134, 0xbfb8aa3b, v134
	v_mul_f32_e32 v132, 0xbfb8aa3b, v132
	v_exp_f32_e32 v138, v134
	v_lshlrev_b32_e32 v134, 16, v135
	v_exp_f32_e32 v139, v132
	v_and_b32_e32 v132, 0xffff0000, v135
	v_mul_f32_e32 v149, 0xbfb8aa3b, v149
	v_mul_f32_e32 v134, 0xbfb8aa3b, v134
	v_mul_f32_e32 v132, 0xbfb8aa3b, v132
	v_exp_f32_e32 v149, v149
	v_exp_f32_e32 v134, v134
	v_exp_f32_e32 v132, v132
	v_pk_add_f32 v[136:137], v[182:183], 1.0 op_sel_hi:[1,0]
	v_add_f32_e32 v149, 1.0, v149
	v_add_f32_e32 v134, 1.0, v134
	v_add_f32_e32 v132, 1.0, v132
	v_rcp_f32_e32 v188, v149
	v_rcp_f32_e32 v134, v134
	v_rcp_f32_e32 v135, v132
	v_pk_add_f32 v[132:133], v[138:139], 1.0 op_sel_hi:[1,0]
	v_pk_mul_f32 v[136:137], v[136:137], v[188:189]
	v_pk_mul_f32 v[184:185], v[184:185], v[186:187]
	v_pk_mul_f32 v[132:133], v[132:133], v[134:135]
	v_pk_mul_f32 v[64:65], v[64:65], v[136:137]
	v_pk_mul_f32 v[66:67], v[66:67], v[132:133]
	v_pk_mul_f32 v[68:69], v[68:69], v[184:185]
	s_nop 0
	v_add_u32_e32 v132, v96, v154
	v_mad_i64_i32 v[132:133], s[12:13], v132, s40, v[98:99]
	v_lshl_add_u64 v[132:133], v[132:133], 0, s[26:27]
	v_lshl_add_u64 v[132:133], v[132:133], 0, v[180:181]
	v_add_co_u32_e32 v136, vcc, s20, v132
	s_nop 1
	v_addc_co_u32_e32 v137, vcc, 0, v133, vcc
	s_waitcnt vmcnt(10)
	v_mov_b32_e32 v182, v216
	v_mov_b32_e32 v183, v217
	v_mov_b32_e32 v184, v218
	v_mov_b32_e32 v185, v219
	v_mov_b32_e32 v186, v220
	v_mov_b32_e32 v187, v221
	v_mov_b32_e32 v188, v222
	v_mov_b32_e32 v189, v223
	s_mov_b32 s98, 0x66000
	s_mov_b32 s99, 0
	v_lshl_add_u64 v[248:249], v[248:249], 0, s[98:99]
	global_load_dwordx4 v[216:219], v[248:249], off offset:-2048
	global_load_dwordx4 v[220:223], v[248:249], off offset:2048
	v_lshlrev_b32_e32 v135, 16, v182
	v_mul_f32_e32 v135, 0xbfb8aa3b, v135
	v_exp_f32_e32 v135, v135
	v_and_b32_e32 v139, 0xffff0000, v182
	v_mul_f32_e32 v139, 0xbfb8aa3b, v139
	v_exp_f32_e32 v139, v139
	v_and_b32_e32 v149, 0xffff0000, v188
	v_add_f32_e32 v135, 1.0, v135
	v_mul_f32_e32 v149, 0xbfb8aa3b, v149
	v_rcp_f32_e32 v138, v135
	v_lshlrev_b32_e32 v135, 16, v188
	v_exp_f32_e32 v197, v149
	v_and_b32_e32 v149, 0xffff0000, v184
	v_mul_f32_e32 v135, 0xbfb8aa3b, v135
	v_mul_f32_e32 v149, 0xbfb8aa3b, v149
	v_exp_f32_e32 v196, v135
	v_lshlrev_b32_e32 v135, 16, v184
	v_exp_f32_e32 v149, v149
	v_mul_f32_e32 v135, 0xbfb8aa3b, v135
	v_exp_f32_e32 v135, v135
	v_lshlrev_b32_e32 v134, 16, v186
	v_add_f32_e32 v149, 1.0, v149
	v_rcp_f32_e32 v199, v149
	v_lshlrev_b32_e32 v149, 16, v187
	v_add_f32_e32 v135, 1.0, v135
	v_mul_f32_e32 v149, 0xbfb8aa3b, v149
	v_rcp_f32_e32 v198, v135
	v_and_b32_e32 v135, 0xffff0000, v186
	v_exp_f32_e32 v186, v149
	v_lshlrev_b32_e32 v149, 16, v183
	v_mul_f32_e32 v149, 0xbfb8aa3b, v149
	v_exp_f32_e32 v149, v149
	v_mul_f32_e32 v134, 0xbfb8aa3b, v134
	v_mul_f32_e32 v135, 0xbfb8aa3b, v135
	v_exp_f32_e32 v134, v134
	v_add_f32_e32 v149, 1.0, v149
	v_rcp_f32_e32 v182, v149
	v_lshlrev_b32_e32 v149, 16, v189
	v_mul_f32_e32 v149, 0xbfb8aa3b, v149
	v_exp_f32_e32 v188, v149
	v_lshlrev_b32_e32 v149, 16, v185
	v_mul_f32_e32 v149, 0xbfb8aa3b, v149
	v_exp_f32_e32 v149, v149
	v_exp_f32_e32 v135, v135
	v_add_f32_e32 v139, 1.0, v139
	v_rcp_f32_e32 v139, v139
	v_add_f32_e32 v149, 1.0, v149
	v_rcp_f32_e32 v184, v149
	v_and_b32_e32 v149, 0xffff0000, v187
	v_pk_add_f32 v[134:135], v[134:135], 1.0 op_sel_hi:[1,0]
	v_mul_f32_e32 v149, 0xbfb8aa3b, v149
	v_pk_mul_f32 v[134:135], v[134:135], v[138:139]
	v_exp_f32_e32 v187, v149
	v_and_b32_e32 v149, 0xffff0000, v183
	v_pk_mul_f32 v[60:61], v[60:61], v[134:135]
	v_and_b32_e32 v134, 0xffff0000, v189
	v_mul_f32_e32 v149, 0xbfb8aa3b, v149
	v_mul_f32_e32 v134, 0xbfb8aa3b, v134
	v_exp_f32_e32 v149, v149
	v_exp_f32_e32 v189, v134
	v_and_b32_e32 v134, 0xffff0000, v185
	v_mul_f32_e32 v134, 0xbfb8aa3b, v134
	v_exp_f32_e32 v134, v134
	v_add_f32_e32 v149, 1.0, v149
	v_rcp_f32_e32 v183, v149
	v_pk_add_f32 v[186:187], v[186:187], 1.0 op_sel_hi:[1,0]
	v_add_f32_e32 v134, 1.0, v134
	v_rcp_f32_e32 v185, v134
	v_pk_mul_f32 v[138:139], v[186:187], v[182:183]
	v_pk_add_f32 v[134:135], v[188:189], 1.0 op_sel_hi:[1,0]
	v_pk_mul_f32 v[62:63], v[62:63], v[138:139]
	v_pk_add_f32 v[138:139], v[196:197], 1.0 op_sel_hi:[1,0]
	v_pk_mul_f32 v[134:135], v[134:135], v[184:185]
	v_pk_mul_f32 v[138:139], v[138:139], v[198:199]
	v_pk_mul_f32 v[58:59], v[58:59], v[134:135]
	v_pk_mul_f32 v[56:57], v[56:57], v[138:139]
	s_nop 0
	s_waitcnt vmcnt(10)
	v_mov_b32_e32 v132, v224
	v_mov_b32_e32 v133, v225
	v_mov_b32_e32 v134, v226
	v_mov_b32_e32 v135, v227
	v_mov_b32_e32 v136, v228
	v_mov_b32_e32 v137, v229
	v_mov_b32_e32 v138, v230
	v_mov_b32_e32 v139, v231
	global_load_dwordx4 v[224:227], v[248:249], off offset:-1792
	global_load_dwordx4 v[228:231], v[248:249], off offset:2304
	v_lshlrev_b32_e32 v149, 16, v136
	v_mul_f32_e32 v149, 0xbfb8aa3b, v149
	v_exp_f32_e32 v184, v149
	v_lshlrev_b32_e32 v149, 16, v132
	v_and_b32_e32 v132, 0xffff0000, v132
	v_mul_f32_e32 v132, 0xbfb8aa3b, v132
	v_exp_f32_e32 v132, v132
	v_and_b32_e32 v136, 0xffff0000, v136
	v_mul_f32_e32 v136, 0xbfb8aa3b, v136
	v_exp_f32_e32 v185, v136
	v_add_f32_e32 v132, 1.0, v132
	v_rcp_f32_e32 v187, v132
	v_and_b32_e32 v132, 0xffff0000, v138
	v_mul_f32_e32 v132, 0xbfb8aa3b, v132
	v_exp_f32_e32 v183, v132
	v_and_b32_e32 v132, 0xffff0000, v134
	v_mul_f32_e32 v132, 0xbfb8aa3b, v132
	v_exp_f32_e32 v132, v132
	v_mul_f32_e32 v149, 0xbfb8aa3b, v149
	v_exp_f32_e32 v149, v149
	v_pk_add_f32 v[184:185], v[184:185], 1.0 op_sel_hi:[1,0]
	v_add_f32_e32 v132, 1.0, v132
	v_rcp_f32_e32 v189, v132
	v_lshlrev_b32_e32 v132, 16, v137
	v_mul_f32_e32 v132, 0xbfb8aa3b, v132
	v_exp_f32_e32 v136, v132
	v_lshlrev_b32_e32 v132, 16, v133
	v_and_b32_e32 v133, 0xffff0000, v133
	v_mul_f32_e32 v132, 0xbfb8aa3b, v132
	v_mul_f32_e32 v133, 0xbfb8aa3b, v133
	v_exp_f32_e32 v132, v132
	v_exp_f32_e32 v133, v133
	v_and_b32_e32 v137, 0xffff0000, v137
	v_mul_f32_e32 v137, 0xbfb8aa3b, v137
	v_add_f32_e32 v132, 1.0, v132
	v_exp_f32_e32 v137, v137
	v_add_f32_e32 v133, 1.0, v133
	v_rcp_f32_e32 v132, v132
	v_rcp_f32_e32 v133, v133
	v_add_f32_e32 v149, 1.0, v149
	v_rcp_f32_e32 v186, v149
	v_lshlrev_b32_e32 v149, 16, v138
	v_pk_add_f32 v[136:137], v[136:137], 1.0 op_sel_hi:[1,0]
	v_mul_f32_e32 v149, 0xbfb8aa3b, v149
	v_pk_mul_f32 v[132:133], v[136:137], v[132:133]
	v_exp_f32_e32 v182, v149
	v_lshlrev_b32_e32 v149, 16, v134
	v_lshlrev_b32_e32 v134, 16, v139
	v_pk_mul_f32 v[54:55], v[54:55], v[132:133]
	v_and_b32_e32 v132, 0xffff0000, v139
	v_mul_f32_e32 v134, 0xbfb8aa3b, v134
	v_mul_f32_e32 v132, 0xbfb8aa3b, v132
	v_exp_f32_e32 v138, v134
	v_lshlrev_b32_e32 v134, 16, v135
	v_exp_f32_e32 v139, v132
	v_and_b32_e32 v132, 0xffff0000, v135
	v_mul_f32_e32 v149, 0xbfb8aa3b, v149
	v_mul_f32_e32 v134, 0xbfb8aa3b, v134
	v_mul_f32_e32 v132, 0xbfb8aa3b, v132
	v_exp_f32_e32 v149, v149
	v_exp_f32_e32 v134, v134
	v_exp_f32_e32 v132, v132
	v_pk_add_f32 v[136:137], v[182:183], 1.0 op_sel_hi:[1,0]
	v_add_f32_e32 v149, 1.0, v149
	v_add_f32_e32 v134, 1.0, v134
	v_add_f32_e32 v132, 1.0, v132
	v_rcp_f32_e32 v188, v149
	v_rcp_f32_e32 v134, v134
	v_rcp_f32_e32 v135, v132
	v_pk_add_f32 v[132:133], v[138:139], 1.0 op_sel_hi:[1,0]
	v_pk_mul_f32 v[136:137], v[136:137], v[188:189]
	v_pk_mul_f32 v[184:185], v[184:185], v[186:187]
	v_pk_mul_f32 v[132:133], v[132:133], v[134:135]
	v_pk_mul_f32 v[48:49], v[48:49], v[136:137]
	v_pk_mul_f32 v[50:51], v[50:51], v[132:133]
	v_pk_mul_f32 v[52:53], v[52:53], v[184:185]
	s_nop 0
	v_add_u32_e32 v132, v96, v152
	v_mad_i64_i32 v[132:133], s[12:13], v132, s40, v[98:99]
	v_lshl_add_u64 v[132:133], v[132:133], 0, s[26:27]
	v_lshl_add_u64 v[132:133], v[132:133], 0, v[180:181]
	v_add_co_u32_e32 v136, vcc, s20, v132
	s_nop 1
	v_addc_co_u32_e32 v137, vcc, 0, v133, vcc
	s_waitcnt vmcnt(10)
	v_mov_b32_e32 v182, v232
	v_mov_b32_e32 v183, v233
	v_mov_b32_e32 v184, v234
	v_mov_b32_e32 v185, v235
	v_mov_b32_e32 v186, v236
	v_mov_b32_e32 v187, v237
	v_mov_b32_e32 v188, v238
	v_mov_b32_e32 v189, v239
	v_lshlrev_b32_e32 v135, 16, v182
	v_mul_f32_e32 v135, 0xbfb8aa3b, v135
	v_exp_f32_e32 v135, v135
	v_and_b32_e32 v139, 0xffff0000, v182
	v_mul_f32_e32 v139, 0xbfb8aa3b, v139
	v_exp_f32_e32 v139, v139
	v_and_b32_e32 v149, 0xffff0000, v188
	v_add_f32_e32 v135, 1.0, v135
	v_mul_f32_e32 v149, 0xbfb8aa3b, v149
	v_rcp_f32_e32 v138, v135
	v_lshlrev_b32_e32 v135, 16, v188
	v_exp_f32_e32 v197, v149
	v_and_b32_e32 v149, 0xffff0000, v184
	v_mul_f32_e32 v135, 0xbfb8aa3b, v135
	v_mul_f32_e32 v149, 0xbfb8aa3b, v149
	v_exp_f32_e32 v196, v135
	v_lshlrev_b32_e32 v135, 16, v184
	v_exp_f32_e32 v149, v149
	v_mul_f32_e32 v135, 0xbfb8aa3b, v135
	v_exp_f32_e32 v135, v135
	v_lshlrev_b32_e32 v134, 16, v186
	v_add_f32_e32 v149, 1.0, v149
	v_rcp_f32_e32 v199, v149
	v_lshlrev_b32_e32 v149, 16, v187
	v_add_f32_e32 v135, 1.0, v135
	v_mul_f32_e32 v149, 0xbfb8aa3b, v149
	v_rcp_f32_e32 v198, v135
	v_and_b32_e32 v135, 0xffff0000, v186
	v_exp_f32_e32 v186, v149
	v_lshlrev_b32_e32 v149, 16, v183
	v_mul_f32_e32 v149, 0xbfb8aa3b, v149
	v_exp_f32_e32 v149, v149
	v_mul_f32_e32 v134, 0xbfb8aa3b, v134
	v_mul_f32_e32 v135, 0xbfb8aa3b, v135
	v_exp_f32_e32 v134, v134
	v_add_f32_e32 v149, 1.0, v149
	v_rcp_f32_e32 v182, v149
	v_lshlrev_b32_e32 v149, 16, v189
	v_mul_f32_e32 v149, 0xbfb8aa3b, v149
	v_exp_f32_e32 v188, v149
	v_lshlrev_b32_e32 v149, 16, v185
	v_mul_f32_e32 v149, 0xbfb8aa3b, v149
	v_exp_f32_e32 v149, v149
	v_exp_f32_e32 v135, v135
	v_add_f32_e32 v139, 1.0, v139
	v_rcp_f32_e32 v139, v139
	v_add_f32_e32 v149, 1.0, v149
	v_rcp_f32_e32 v184, v149
	v_and_b32_e32 v149, 0xffff0000, v187
	v_pk_add_f32 v[134:135], v[134:135], 1.0 op_sel_hi:[1,0]
	v_mul_f32_e32 v149, 0xbfb8aa3b, v149
	v_pk_mul_f32 v[134:135], v[134:135], v[138:139]
	v_exp_f32_e32 v187, v149
	v_and_b32_e32 v149, 0xffff0000, v183
	v_pk_mul_f32 v[44:45], v[44:45], v[134:135]
	v_and_b32_e32 v134, 0xffff0000, v189
	v_mul_f32_e32 v149, 0xbfb8aa3b, v149
	v_mul_f32_e32 v134, 0xbfb8aa3b, v134
	v_exp_f32_e32 v149, v149
	v_exp_f32_e32 v189, v134
	v_and_b32_e32 v134, 0xffff0000, v185
	v_mul_f32_e32 v134, 0xbfb8aa3b, v134
	v_exp_f32_e32 v134, v134
	v_add_f32_e32 v149, 1.0, v149
	v_rcp_f32_e32 v183, v149
	v_pk_add_f32 v[186:187], v[186:187], 1.0 op_sel_hi:[1,0]
	v_add_f32_e32 v134, 1.0, v134
	v_rcp_f32_e32 v185, v134
	v_pk_mul_f32 v[138:139], v[186:187], v[182:183]
	v_pk_add_f32 v[134:135], v[188:189], 1.0 op_sel_hi:[1,0]
	v_pk_mul_f32 v[46:47], v[46:47], v[138:139]
	v_pk_add_f32 v[138:139], v[196:197], 1.0 op_sel_hi:[1,0]
	v_pk_mul_f32 v[134:135], v[134:135], v[184:185]
	v_pk_mul_f32 v[138:139], v[138:139], v[198:199]
	v_pk_mul_f32 v[42:43], v[42:43], v[134:135]
	v_pk_mul_f32 v[40:41], v[40:41], v[138:139]
	s_nop 0
	s_waitcnt vmcnt(8)
	v_mov_b32_e32 v132, v240
	v_mov_b32_e32 v133, v241
	v_mov_b32_e32 v134, v242
	v_mov_b32_e32 v135, v243
	v_mov_b32_e32 v136, v244
	v_mov_b32_e32 v137, v245
	v_mov_b32_e32 v138, v246
	v_mov_b32_e32 v139, v247
	v_lshlrev_b32_e32 v149, 16, v136
	v_mul_f32_e32 v149, 0xbfb8aa3b, v149
	v_exp_f32_e32 v184, v149
	v_lshlrev_b32_e32 v149, 16, v132
	v_and_b32_e32 v132, 0xffff0000, v132
	v_mul_f32_e32 v132, 0xbfb8aa3b, v132
	v_exp_f32_e32 v132, v132
	v_and_b32_e32 v136, 0xffff0000, v136
	v_mul_f32_e32 v136, 0xbfb8aa3b, v136
	v_exp_f32_e32 v185, v136
	v_add_f32_e32 v132, 1.0, v132
	v_rcp_f32_e32 v187, v132
	v_and_b32_e32 v132, 0xffff0000, v138
	v_mul_f32_e32 v132, 0xbfb8aa3b, v132
	v_exp_f32_e32 v183, v132
	v_and_b32_e32 v132, 0xffff0000, v134
	v_mul_f32_e32 v132, 0xbfb8aa3b, v132
	v_exp_f32_e32 v132, v132
	v_mul_f32_e32 v149, 0xbfb8aa3b, v149
	v_exp_f32_e32 v149, v149
	v_pk_add_f32 v[184:185], v[184:185], 1.0 op_sel_hi:[1,0]
	v_add_f32_e32 v132, 1.0, v132
	v_rcp_f32_e32 v189, v132
	v_lshlrev_b32_e32 v132, 16, v137
	v_mul_f32_e32 v132, 0xbfb8aa3b, v132
	v_exp_f32_e32 v136, v132
	v_lshlrev_b32_e32 v132, 16, v133
	v_and_b32_e32 v133, 0xffff0000, v133
	v_mul_f32_e32 v132, 0xbfb8aa3b, v132
	v_mul_f32_e32 v133, 0xbfb8aa3b, v133
	v_exp_f32_e32 v132, v132
	v_exp_f32_e32 v133, v133
	v_and_b32_e32 v137, 0xffff0000, v137
	v_mul_f32_e32 v137, 0xbfb8aa3b, v137
	v_add_f32_e32 v132, 1.0, v132
	v_exp_f32_e32 v137, v137
	v_add_f32_e32 v133, 1.0, v133
	v_rcp_f32_e32 v132, v132
	v_rcp_f32_e32 v133, v133
	v_add_f32_e32 v149, 1.0, v149
	v_rcp_f32_e32 v186, v149
	v_lshlrev_b32_e32 v149, 16, v138
	v_pk_add_f32 v[136:137], v[136:137], 1.0 op_sel_hi:[1,0]
	v_mul_f32_e32 v149, 0xbfb8aa3b, v149
	v_pk_mul_f32 v[132:133], v[136:137], v[132:133]
	v_exp_f32_e32 v182, v149
	v_lshlrev_b32_e32 v149, 16, v134
	v_lshlrev_b32_e32 v134, 16, v139
	v_pk_mul_f32 v[38:39], v[38:39], v[132:133]
	v_and_b32_e32 v132, 0xffff0000, v139
	v_mul_f32_e32 v134, 0xbfb8aa3b, v134
	v_mul_f32_e32 v132, 0xbfb8aa3b, v132
	v_exp_f32_e32 v138, v134
	v_lshlrev_b32_e32 v134, 16, v135
	v_exp_f32_e32 v139, v132
	v_and_b32_e32 v132, 0xffff0000, v135
	v_mul_f32_e32 v149, 0xbfb8aa3b, v149
	v_mul_f32_e32 v134, 0xbfb8aa3b, v134
	v_mul_f32_e32 v132, 0xbfb8aa3b, v132
	v_exp_f32_e32 v149, v149
	v_exp_f32_e32 v134, v134
	v_exp_f32_e32 v132, v132
	v_pk_add_f32 v[136:137], v[182:183], 1.0 op_sel_hi:[1,0]
	v_add_f32_e32 v149, 1.0, v149
	v_add_f32_e32 v134, 1.0, v134
	v_add_f32_e32 v132, 1.0, v132
	v_rcp_f32_e32 v188, v149
	v_rcp_f32_e32 v134, v134
	v_rcp_f32_e32 v135, v132
	v_pk_add_f32 v[132:133], v[138:139], 1.0 op_sel_hi:[1,0]
	v_pk_mul_f32 v[136:137], v[136:137], v[188:189]
	v_pk_mul_f32 v[184:185], v[184:185], v[186:187]
	v_pk_mul_f32 v[132:133], v[132:133], v[134:135]
	v_pk_mul_f32 v[32:33], v[32:33], v[136:137]
	v_pk_mul_f32 v[34:35], v[34:35], v[132:133]
	v_pk_mul_f32 v[36:37], v[36:37], v[184:185]
	s_nop 0
	v_add_u32_e32 v132, v96, v150
	v_mad_i64_i32 v[132:133], s[12:13], v132, s40, v[98:99]
	v_lshl_add_u64 v[132:133], v[132:133], 0, s[26:27]
	v_lshl_add_u64 v[132:133], v[132:133], 0, v[180:181]
	v_add_co_u32_e32 v136, vcc, s20, v132
	s_nop 1
	v_addc_co_u32_e32 v137, vcc, 0, v133, vcc
	s_waitcnt vmcnt(6)
	v_mov_b32_e32 v182, v200
	v_mov_b32_e32 v183, v201
	v_mov_b32_e32 v184, v202
	v_mov_b32_e32 v185, v203
	v_mov_b32_e32 v186, v204
	v_mov_b32_e32 v187, v205
	v_mov_b32_e32 v188, v206
	v_mov_b32_e32 v189, v207
	v_lshlrev_b32_e32 v135, 16, v182
	v_mul_f32_e32 v135, 0xbfb8aa3b, v135
	v_exp_f32_e32 v135, v135
	v_and_b32_e32 v139, 0xffff0000, v182
	v_mul_f32_e32 v139, 0xbfb8aa3b, v139
	v_exp_f32_e32 v139, v139
	v_and_b32_e32 v149, 0xffff0000, v188
	v_add_f32_e32 v135, 1.0, v135
	v_mul_f32_e32 v149, 0xbfb8aa3b, v149
	v_rcp_f32_e32 v138, v135
	v_lshlrev_b32_e32 v135, 16, v188
	v_exp_f32_e32 v197, v149
	v_and_b32_e32 v149, 0xffff0000, v184
	v_mul_f32_e32 v135, 0xbfb8aa3b, v135
	v_mul_f32_e32 v149, 0xbfb8aa3b, v149
	v_exp_f32_e32 v196, v135
	v_lshlrev_b32_e32 v135, 16, v184
	v_exp_f32_e32 v149, v149
	v_mul_f32_e32 v135, 0xbfb8aa3b, v135
	v_exp_f32_e32 v135, v135
	v_lshlrev_b32_e32 v134, 16, v186
	v_add_f32_e32 v149, 1.0, v149
	v_rcp_f32_e32 v199, v149
	v_lshlrev_b32_e32 v149, 16, v187
	v_add_f32_e32 v135, 1.0, v135
	v_mul_f32_e32 v149, 0xbfb8aa3b, v149
	v_rcp_f32_e32 v198, v135
	v_and_b32_e32 v135, 0xffff0000, v186
	v_exp_f32_e32 v186, v149
	v_lshlrev_b32_e32 v149, 16, v183
	v_mul_f32_e32 v149, 0xbfb8aa3b, v149
	v_exp_f32_e32 v149, v149
	v_mul_f32_e32 v134, 0xbfb8aa3b, v134
	v_mul_f32_e32 v135, 0xbfb8aa3b, v135
	v_exp_f32_e32 v134, v134
	v_add_f32_e32 v149, 1.0, v149
	v_rcp_f32_e32 v182, v149
	v_lshlrev_b32_e32 v149, 16, v189
	v_mul_f32_e32 v149, 0xbfb8aa3b, v149
	v_exp_f32_e32 v188, v149
	v_lshlrev_b32_e32 v149, 16, v185
	v_mul_f32_e32 v149, 0xbfb8aa3b, v149
	v_exp_f32_e32 v149, v149
	v_exp_f32_e32 v135, v135
	v_add_f32_e32 v139, 1.0, v139
	v_rcp_f32_e32 v139, v139
	v_add_f32_e32 v149, 1.0, v149
	v_rcp_f32_e32 v184, v149
	v_and_b32_e32 v149, 0xffff0000, v187
	v_pk_add_f32 v[134:135], v[134:135], 1.0 op_sel_hi:[1,0]
	v_mul_f32_e32 v149, 0xbfb8aa3b, v149
	v_pk_mul_f32 v[134:135], v[134:135], v[138:139]
	v_exp_f32_e32 v187, v149
	v_and_b32_e32 v149, 0xffff0000, v183
	v_pk_mul_f32 v[28:29], v[28:29], v[134:135]
	v_and_b32_e32 v134, 0xffff0000, v189
	v_mul_f32_e32 v149, 0xbfb8aa3b, v149
	v_mul_f32_e32 v134, 0xbfb8aa3b, v134
	v_exp_f32_e32 v149, v149
	v_exp_f32_e32 v189, v134
	v_and_b32_e32 v134, 0xffff0000, v185
	v_mul_f32_e32 v134, 0xbfb8aa3b, v134
	v_exp_f32_e32 v134, v134
	v_add_f32_e32 v149, 1.0, v149
	v_rcp_f32_e32 v183, v149
	v_pk_add_f32 v[186:187], v[186:187], 1.0 op_sel_hi:[1,0]
	v_add_f32_e32 v134, 1.0, v134
	v_rcp_f32_e32 v185, v134
	v_pk_mul_f32 v[138:139], v[186:187], v[182:183]
	v_pk_add_f32 v[134:135], v[188:189], 1.0 op_sel_hi:[1,0]
	v_pk_mul_f32 v[30:31], v[30:31], v[138:139]
	v_pk_add_f32 v[138:139], v[196:197], 1.0 op_sel_hi:[1,0]
	v_pk_mul_f32 v[134:135], v[134:135], v[184:185]
	v_pk_mul_f32 v[138:139], v[138:139], v[198:199]
	v_pk_mul_f32 v[26:27], v[26:27], v[134:135]
	v_pk_mul_f32 v[24:25], v[24:25], v[138:139]
	s_nop 0
	s_waitcnt vmcnt(4)
	v_mov_b32_e32 v132, v208
	v_mov_b32_e32 v133, v209
	v_mov_b32_e32 v134, v210
	v_mov_b32_e32 v135, v211
	v_mov_b32_e32 v136, v212
	v_mov_b32_e32 v137, v213
	v_mov_b32_e32 v138, v214
	v_mov_b32_e32 v139, v215
	v_lshlrev_b32_e32 v149, 16, v136
	v_mul_f32_e32 v149, 0xbfb8aa3b, v149
	v_exp_f32_e32 v184, v149
	v_lshlrev_b32_e32 v149, 16, v132
	v_and_b32_e32 v132, 0xffff0000, v132
	v_mul_f32_e32 v132, 0xbfb8aa3b, v132
	v_exp_f32_e32 v132, v132
	v_and_b32_e32 v136, 0xffff0000, v136
	v_mul_f32_e32 v136, 0xbfb8aa3b, v136
	v_exp_f32_e32 v185, v136
	v_add_f32_e32 v132, 1.0, v132
	v_rcp_f32_e32 v187, v132
	v_and_b32_e32 v132, 0xffff0000, v138
	v_mul_f32_e32 v132, 0xbfb8aa3b, v132
	v_exp_f32_e32 v183, v132
	v_and_b32_e32 v132, 0xffff0000, v134
	v_mul_f32_e32 v132, 0xbfb8aa3b, v132
	v_exp_f32_e32 v132, v132
	v_mul_f32_e32 v149, 0xbfb8aa3b, v149
	v_exp_f32_e32 v149, v149
	v_pk_add_f32 v[184:185], v[184:185], 1.0 op_sel_hi:[1,0]
	v_add_f32_e32 v132, 1.0, v132
	v_rcp_f32_e32 v189, v132
	v_lshlrev_b32_e32 v132, 16, v137
	v_mul_f32_e32 v132, 0xbfb8aa3b, v132
	v_exp_f32_e32 v136, v132
	v_lshlrev_b32_e32 v132, 16, v133
	v_and_b32_e32 v133, 0xffff0000, v133
	v_mul_f32_e32 v132, 0xbfb8aa3b, v132
	v_mul_f32_e32 v133, 0xbfb8aa3b, v133
	v_exp_f32_e32 v132, v132
	v_exp_f32_e32 v133, v133
	v_and_b32_e32 v137, 0xffff0000, v137
	v_mul_f32_e32 v137, 0xbfb8aa3b, v137
	v_add_f32_e32 v132, 1.0, v132
	v_exp_f32_e32 v137, v137
	v_add_f32_e32 v133, 1.0, v133
	v_rcp_f32_e32 v132, v132
	v_rcp_f32_e32 v133, v133
	v_add_f32_e32 v149, 1.0, v149
	v_rcp_f32_e32 v186, v149
	v_lshlrev_b32_e32 v149, 16, v138
	v_pk_add_f32 v[136:137], v[136:137], 1.0 op_sel_hi:[1,0]
	v_mul_f32_e32 v149, 0xbfb8aa3b, v149
	v_pk_mul_f32 v[132:133], v[136:137], v[132:133]
	v_exp_f32_e32 v182, v149
	v_lshlrev_b32_e32 v149, 16, v134
	v_lshlrev_b32_e32 v134, 16, v139
	v_pk_mul_f32 v[22:23], v[22:23], v[132:133]
	v_and_b32_e32 v132, 0xffff0000, v139
	v_mul_f32_e32 v134, 0xbfb8aa3b, v134
	v_mul_f32_e32 v132, 0xbfb8aa3b, v132
	v_exp_f32_e32 v138, v134
	v_lshlrev_b32_e32 v134, 16, v135
	v_exp_f32_e32 v139, v132
	v_and_b32_e32 v132, 0xffff0000, v135
	v_mul_f32_e32 v149, 0xbfb8aa3b, v149
	v_mul_f32_e32 v134, 0xbfb8aa3b, v134
	v_mul_f32_e32 v132, 0xbfb8aa3b, v132
	v_exp_f32_e32 v149, v149
	v_exp_f32_e32 v134, v134
	v_exp_f32_e32 v132, v132
	v_pk_add_f32 v[136:137], v[182:183], 1.0 op_sel_hi:[1,0]
	v_add_f32_e32 v149, 1.0, v149
	v_add_f32_e32 v134, 1.0, v134
	v_add_f32_e32 v132, 1.0, v132
	v_rcp_f32_e32 v188, v149
	v_rcp_f32_e32 v134, v134
	v_rcp_f32_e32 v135, v132
	v_pk_add_f32 v[132:133], v[138:139], 1.0 op_sel_hi:[1,0]
	v_pk_mul_f32 v[136:137], v[136:137], v[188:189]
	v_pk_mul_f32 v[184:185], v[184:185], v[186:187]
	v_pk_mul_f32 v[132:133], v[132:133], v[134:135]
	v_pk_mul_f32 v[16:17], v[16:17], v[136:137]
	v_pk_mul_f32 v[18:19], v[18:19], v[132:133]
	v_pk_mul_f32 v[20:21], v[20:21], v[184:185]
	s_nop 0
	v_add_u32_e32 v132, v96, v148
	v_mad_i64_i32 v[98:99], s[12:13], v132, s40, v[98:99]
	v_lshl_add_u64 v[98:99], v[98:99], 0, s[26:27]
	v_lshl_add_u64 v[132:133], v[98:99], 0, v[180:181]
	v_add_co_u32_e32 v98, vcc, s20, v132
	s_nop 1
	v_addc_co_u32_e32 v99, vcc, 0, v133, vcc
	s_waitcnt vmcnt(2)
	v_mov_b32_e32 v134, v216
	v_mov_b32_e32 v135, v217
	v_mov_b32_e32 v136, v218
	v_mov_b32_e32 v137, v219
	v_mov_b32_e32 v180, v220
	v_mov_b32_e32 v181, v221
	v_mov_b32_e32 v182, v222
	v_mov_b32_e32 v183, v223
	v_lshlrev_b32_e32 v139, 16, v134
	v_and_b32_e32 v134, 0xffff0000, v134
	v_mul_f32_e32 v134, 0xbfb8aa3b, v134
	v_exp_f32_e32 v134, v134
	v_mul_f32_e32 v139, 0xbfb8aa3b, v139
	v_exp_f32_e32 v139, v139
	v_lshlrev_b32_e32 v138, 16, v180
	v_add_f32_e32 v134, 1.0, v134
	v_rcp_f32_e32 v185, v134
	v_and_b32_e32 v134, 0xffff0000, v182
	v_add_f32_e32 v139, 1.0, v139
	v_mul_f32_e32 v134, 0xbfb8aa3b, v134
	v_rcp_f32_e32 v184, v139
	v_lshlrev_b32_e32 v139, 16, v182
	v_exp_f32_e32 v187, v134
	v_and_b32_e32 v134, 0xffff0000, v136
	v_mul_f32_e32 v139, 0xbfb8aa3b, v139
	v_mul_f32_e32 v134, 0xbfb8aa3b, v134
	v_exp_f32_e32 v186, v139
	v_lshlrev_b32_e32 v139, 16, v136
	v_exp_f32_e32 v134, v134
	v_mul_f32_e32 v139, 0xbfb8aa3b, v139
	v_exp_f32_e32 v139, v139
	v_and_b32_e32 v149, 0xffff0000, v181
	v_add_f32_e32 v134, 1.0, v134
	v_rcp_f32_e32 v189, v134
	v_lshlrev_b32_e32 v134, 16, v181
	v_add_f32_e32 v139, 1.0, v139
	v_mul_f32_e32 v134, 0xbfb8aa3b, v134
	v_rcp_f32_e32 v188, v139
	v_and_b32_e32 v139, 0xffff0000, v180
	v_exp_f32_e32 v180, v134
	v_lshlrev_b32_e32 v134, 16, v135
	v_and_b32_e32 v135, 0xffff0000, v135
	v_mul_f32_e32 v134, 0xbfb8aa3b, v134
	v_mul_f32_e32 v135, 0xbfb8aa3b, v135
	v_exp_f32_e32 v134, v134
	v_exp_f32_e32 v135, v135
	v_mul_f32_e32 v149, 0xbfb8aa3b, v149
	v_exp_f32_e32 v181, v149
	v_add_f32_e32 v134, 1.0, v134
	v_add_f32_e32 v135, 1.0, v135
	v_rcp_f32_e32 v134, v134
	v_rcp_f32_e32 v135, v135
	v_pk_add_f32 v[180:181], v[180:181], 1.0 op_sel_hi:[1,0]
	v_lshlrev_b32_e32 v136, 16, v183
	v_mul_f32_e32 v136, 0xbfb8aa3b, v136
	v_pk_mul_f32 v[134:135], v[180:181], v[134:135]
	v_exp_f32_e32 v182, v136
	v_pk_mul_f32 v[14:15], v[14:15], v[134:135]
	v_and_b32_e32 v134, 0xffff0000, v183
	v_mul_f32_e32 v134, 0xbfb8aa3b, v134
	v_lshlrev_b32_e32 v136, 16, v137
	v_exp_f32_e32 v183, v134
	v_and_b32_e32 v134, 0xffff0000, v137
	v_mul_f32_e32 v136, 0xbfb8aa3b, v136
	v_mul_f32_e32 v134, 0xbfb8aa3b, v134
	v_exp_f32_e32 v136, v136
	v_exp_f32_e32 v134, v134
	v_mul_f32_e32 v138, 0xbfb8aa3b, v138
	v_mul_f32_e32 v139, 0xbfb8aa3b, v139
	v_exp_f32_e32 v138, v138
	v_exp_f32_e32 v139, v139
	v_add_f32_e32 v136, 1.0, v136
	v_add_f32_e32 v134, 1.0, v134
	v_rcp_f32_e32 v136, v136
	v_rcp_f32_e32 v137, v134
	v_pk_add_f32 v[138:139], v[138:139], 1.0 op_sel_hi:[1,0]
	v_pk_add_f32 v[134:135], v[182:183], 1.0 op_sel_hi:[1,0]
	v_pk_mul_f32 v[138:139], v[138:139], v[184:185]
	v_pk_mul_f32 v[134:135], v[134:135], v[136:137]
	v_pk_mul_f32 v[12:13], v[12:13], v[138:139]
	v_pk_add_f32 v[138:139], v[186:187], 1.0 op_sel_hi:[1,0]
	v_pk_mul_f32 v[10:11], v[10:11], v[134:135]
	v_pk_mul_f32 v[138:139], v[138:139], v[188:189]
	s_nop 0
	v_pk_mul_f32 v[8:9], v[8:9], v[138:139]
	s_nop 0
	s_waitcnt vmcnt(0)
	v_mov_b32_e32 v132, v224
	v_mov_b32_e32 v133, v225
	v_mov_b32_e32 v134, v226
	v_mov_b32_e32 v135, v227
	v_mov_b32_e32 v136, v228
	v_mov_b32_e32 v137, v229
	v_mov_b32_e32 v138, v230
	v_mov_b32_e32 v139, v231
	v_lshlrev_b32_e32 v99, 16, v132
	v_mul_f32_e32 v99, 0xbfb8aa3b, v99
	v_exp_f32_e32 v99, v99
	v_and_b32_e32 v132, 0xffff0000, v132
	v_mul_f32_e32 v132, 0xbfb8aa3b, v132
	v_exp_f32_e32 v132, v132
	v_add_f32_e32 v99, 1.0, v99
	v_rcp_f32_e32 v180, v99
	v_lshlrev_b32_e32 v99, 16, v138
	v_mul_f32_e32 v99, 0xbfb8aa3b, v99
	v_exp_f32_e32 v182, v99
	v_lshlrev_b32_e32 v99, 16, v134
	v_mul_f32_e32 v99, 0xbfb8aa3b, v99
	v_exp_f32_e32 v99, v99
	v_add_f32_e32 v132, 1.0, v132
	v_rcp_f32_e32 v181, v132
	v_and_b32_e32 v132, 0xffff0000, v138
	v_mul_f32_e32 v132, 0xbfb8aa3b, v132
	v_add_f32_e32 v99, 1.0, v99
	v_exp_f32_e32 v183, v132
	v_and_b32_e32 v132, 0xffff0000, v134
	v_lshlrev_b32_e32 v98, 16, v136
	v_rcp_f32_e32 v184, v99
	v_and_b32_e32 v99, 0xffff0000, v136
	v_mul_f32_e32 v132, 0xbfb8aa3b, v132
	v_mul_f32_e32 v98, 0xbfb8aa3b, v98
	v_mul_f32_e32 v99, 0xbfb8aa3b, v99
	v_exp_f32_e32 v132, v132
	v_exp_f32_e32 v98, v98
	v_exp_f32_e32 v99, v99
	v_lshlrev_b32_e32 v134, 16, v139
	v_add_f32_e32 v132, 1.0, v132
	v_rcp_f32_e32 v185, v132
	v_lshlrev_b32_e32 v132, 16, v137
	v_pk_add_f32 v[98:99], v[98:99], 1.0 op_sel_hi:[1,0]
	v_mul_f32_e32 v132, 0xbfb8aa3b, v132
	v_pk_mul_f32 v[98:99], v[98:99], v[180:181]
	v_exp_f32_e32 v136, v132
	v_lshlrev_b32_e32 v132, 16, v133
	v_and_b32_e32 v133, 0xffff0000, v133
	v_pk_mul_f32 v[4:5], v[4:5], v[98:99]
	v_and_b32_e32 v98, 0xffff0000, v139
	v_mul_f32_e32 v132, 0xbfb8aa3b, v132
	v_mul_f32_e32 v134, 0xbfb8aa3b, v134
	v_mul_f32_e32 v133, 0xbfb8aa3b, v133
	v_mul_f32_e32 v98, 0xbfb8aa3b, v98
	v_exp_f32_e32 v132, v132
	v_exp_f32_e32 v138, v134
	v_lshlrev_b32_e32 v134, 16, v135
	v_exp_f32_e32 v133, v133
	v_exp_f32_e32 v139, v98
	v_and_b32_e32 v98, 0xffff0000, v135
	v_mul_f32_e32 v134, 0xbfb8aa3b, v134
	v_mul_f32_e32 v98, 0xbfb8aa3b, v98
	v_exp_f32_e32 v134, v134
	v_and_b32_e32 v137, 0xffff0000, v137
	v_exp_f32_e32 v98, v98
	v_mul_f32_e32 v137, 0xbfb8aa3b, v137
	v_add_f32_e32 v132, 1.0, v132
	v_exp_f32_e32 v137, v137
	v_add_f32_e32 v133, 1.0, v133
	v_rcp_f32_e32 v132, v132
	v_rcp_f32_e32 v133, v133
	v_add_f32_e32 v134, 1.0, v134
	v_add_f32_e32 v98, 1.0, v98
	v_rcp_f32_e32 v134, v134
	v_rcp_f32_e32 v135, v98
	v_pk_add_f32 v[136:137], v[136:137], 1.0 op_sel_hi:[1,0]
	v_pk_add_f32 v[98:99], v[138:139], 1.0 op_sel_hi:[1,0]
	v_pk_mul_f32 v[132:133], v[136:137], v[132:133]
	v_pk_mul_f32 v[98:99], v[98:99], v[134:135]
	v_pk_mul_f32 v[6:7], v[6:7], v[132:133]
	v_pk_add_f32 v[132:133], v[182:183], 1.0 op_sel_hi:[1,0]
	v_pk_mul_f32 v[2:3], v[2:3], v[98:99]
	v_pk_mul_f32 v[132:133], v[132:133], v[184:185]
	s_nop 0
	v_pk_mul_f32 v[0:1], v[0:1], v[132:133]
	s_nop 0
	s_branch .LBB0_959

.LBB0_967:
	v_lshl_add_u64 v[248:249], v[174:175], 1, v[176:177]
	v_lshl_add_u64 v[248:249], v[248:249], 0, s[8:9]
	global_load_dwordx4 v[200:203], v[248:249], off
	global_load_dwordx4 v[204:207], v[248:249], off offset:256
	s_mov_b32 s98, 0x66000
	s_mov_b32 s99, 0
	v_lshl_add_u64 v[248:249], v[248:249], 0, s[98:99]
	global_load_dwordx4 v[208:211], v[248:249], off
	global_load_dwordx4 v[212:215], v[248:249], off offset:256
	s_mov_b32 s98, 0x66000
	s_mov_b32 s99, 0
	v_lshl_add_u64 v[248:249], v[248:249], 0, s[98:99]
	global_load_dwordx4 v[216:219], v[248:249], off
	global_load_dwordx4 v[220:223], v[248:249], off offset:256
	v_lshlrev_b64 v[98:99], 1, v[174:175]
	v_lshl_add_u64 v[136:137], v[176:177], 0, v[98:99]
	v_lshl_add_u64 v[132:133], v[136:137], 0, s[8:9]
	v_add_co_u32_e32 v136, vcc, 0x2000, v136
	v_lshlrev_b64 v[134:135], 12, v[172:173]
	s_nop 0
	v_addc_co_u32_e32 v137, vcc, 0, v137, vcc
	v_ashrrev_i32_e32 v171, 31, v170
	v_ashrrev_i32_e32 v169, 31, v168
	v_ashrrev_i32_e32 v157, 31, v156
	v_ashrrev_i32_e32 v155, 31, v154
	v_ashrrev_i32_e32 v153, 31, v152
	v_ashrrev_i32_e32 v151, 31, v150
	v_ashrrev_i32_e32 v149, 31, v148
	v_readlane_b32 s68, v255, 46
	v_readlane_b32 s69, v255, 47
	s_nop 1
	s_waitcnt vmcnt(5)
	v_mov_b32_e32 v136, v200
	v_mov_b32_e32 v137, v201
	v_mov_b32_e32 v138, v202
	v_mov_b32_e32 v139, v203
	s_mov_b32 s98, 0x66000
	s_mov_b32 s99, 0
	v_lshl_add_u64 v[248:249], v[248:249], 0, s[98:99]
	global_load_dwordx4 v[200:203], v[248:249], off
	v_lshlrev_b32_e32 v96, 16, v136
	v_mul_f32_e32 v96, 0xbfb8aa3b, v96
	v_exp_f32_e32 v96, v96
	s_nop 0
	v_add_f32_e32 v96, 1.0, v96
	v_rcp_f32_e32 v96, v96
	s_nop 0
	v_mul_f32_e32 v96, v128, v96
	v_lshlrev_b32_e32 v128, 16, v138
	v_mul_f32_e32 v128, 0xbfb8aa3b, v128
	v_exp_f32_e32 v128, v128
	s_nop 0
	v_add_f32_e32 v128, 1.0, v128
	v_rcp_f32_e32 v128, v128
	s_nop 0
	v_mul_f32_e32 v128, v124, v128
	v_and_b32_e32 v124, 0xffff0000, v136
	v_mul_f32_e32 v124, 0xbfb8aa3b, v124
	v_exp_f32_e32 v124, v124
	s_nop 0
	v_add_f32_e32 v124, 1.0, v124
	v_rcp_f32_e32 v124, v124
	s_nop 0
	v_mul_f32_e32 v129, v129, v124
	v_and_b32_e32 v124, 0xffff0000, v138
	v_mul_f32_e32 v124, 0xbfb8aa3b, v124
	v_exp_f32_e32 v124, v124
	s_nop 0
	v_add_f32_e32 v124, 1.0, v124
	v_rcp_f32_e32 v124, v124
	s_nop 0
	v_mul_f32_e32 v136, v125, v124
	v_lshlrev_b32_e32 v124, 16, v137
	v_mul_f32_e32 v124, 0xbfb8aa3b, v124
	v_exp_f32_e32 v124, v124
	s_nop 0
	v_add_f32_e32 v124, 1.0, v124
	v_rcp_f32_e32 v124, v124
	s_nop 0
	v_mul_f32_e32 v130, v130, v124
	v_lshlrev_b32_e32 v124, 16, v139
	v_mul_f32_e32 v124, 0xbfb8aa3b, v124
	v_exp_f32_e32 v124, v124
	s_nop 0
	v_add_f32_e32 v124, 1.0, v124
	v_rcp_f32_e32 v124, v124
	s_nop 0
	v_mul_f32_e32 v138, v126, v124
	v_and_b32_e32 v124, 0xffff0000, v137
	v_mul_f32_e32 v124, 0xbfb8aa3b, v124
	v_exp_f32_e32 v124, v124
	v_cvt_pk_bf16_f32 v126, v96, v129
	s_nop 0
	v_add_f32_e32 v124, 1.0, v124
	v_rcp_f32_e32 v124, v124
	s_nop 0
	v_mul_f32_e32 v131, v131, v124
	v_and_b32_e32 v124, 0xffff0000, v139
	v_mul_f32_e32 v124, 0xbfb8aa3b, v124
	v_exp_f32_e32 v124, v124
	s_nop 0
	v_add_f32_e32 v124, 1.0, v124
	v_rcp_f32_e32 v124, v124
	s_nop 0
	v_mul_f32_e32 v137, v127, v124
	v_lshl_add_u64 v[124:125], s[48:49], 0, v[134:135]
	v_lshl_add_u64 v[124:125], v[124:125], 0, v[98:99]
	v_cvt_pk_bf16_f32 v127, v130, v131
	v_cvt_pk_bf16_f32 v128, v128, v136
	v_cvt_pk_bf16_f32 v129, v138, v137
	global_store_dwordx4 v[124:125], v[126:129], off
	s_nop 1
	s_waitcnt vmcnt(6)
	v_mov_b32_e32 v126, v204
	v_mov_b32_e32 v127, v205
	v_mov_b32_e32 v128, v206
	v_mov_b32_e32 v129, v207
	global_load_dwordx4 v[204:207], v[248:249], off offset:256
	v_lshlrev_b32_e32 v96, 16, v126
	v_mul_f32_e32 v96, 0xbfb8aa3b, v96
	v_exp_f32_e32 v96, v96
	s_nop 0
	v_add_f32_e32 v96, 1.0, v96
	v_rcp_f32_e32 v96, v96
	s_nop 0
	v_mul_f32_e32 v96, v120, v96
	v_lshlrev_b32_e32 v120, 16, v128
	v_mul_f32_e32 v120, 0xbfb8aa3b, v120
	v_exp_f32_e32 v120, v120
	s_nop 0
	v_add_f32_e32 v120, 1.0, v120
	v_rcp_f32_e32 v120, v120
	s_nop 0
	v_mul_f32_e32 v120, v116, v120
	v_and_b32_e32 v116, 0xffff0000, v126
	v_mul_f32_e32 v116, 0xbfb8aa3b, v116
	v_exp_f32_e32 v116, v116
	s_nop 0
	v_add_f32_e32 v116, 1.0, v116
	v_rcp_f32_e32 v116, v116
	s_nop 0
	v_mul_f32_e32 v116, v121, v116
	v_and_b32_e32 v121, 0xffff0000, v128
	v_mul_f32_e32 v121, 0xbfb8aa3b, v121
	v_exp_f32_e32 v121, v121
	v_cvt_pk_bf16_f32 v116, v96, v116
	s_nop 0
	v_add_f32_e32 v121, 1.0, v121
	v_rcp_f32_e32 v121, v121
	s_nop 0
	v_mul_f32_e32 v121, v117, v121
	v_lshlrev_b32_e32 v117, 16, v127
	v_mul_f32_e32 v117, 0xbfb8aa3b, v117
	v_exp_f32_e32 v117, v117
	s_nop 0
	v_add_f32_e32 v117, 1.0, v117
	v_rcp_f32_e32 v117, v117
	s_nop 0
	v_mul_f32_e32 v117, v122, v117
	v_lshlrev_b32_e32 v122, 16, v129
	v_mul_f32_e32 v122, 0xbfb8aa3b, v122
	v_exp_f32_e32 v122, v122
	s_nop 0
	v_add_f32_e32 v122, 1.0, v122
	v_rcp_f32_e32 v122, v122
	s_nop 0
	v_mul_f32_e32 v122, v118, v122
	v_and_b32_e32 v118, 0xffff0000, v127
	v_mul_f32_e32 v118, 0xbfb8aa3b, v118
	v_exp_f32_e32 v118, v118
	s_nop 0
	v_add_f32_e32 v118, 1.0, v118
	v_rcp_f32_e32 v118, v118
	s_nop 0
	v_mul_f32_e32 v118, v123, v118
	v_and_b32_e32 v123, 0xffff0000, v129
	v_mul_f32_e32 v123, 0xbfb8aa3b, v123
	v_exp_f32_e32 v123, v123
	v_cvt_pk_bf16_f32 v117, v117, v118
	v_cvt_pk_bf16_f32 v118, v120, v121
	v_lshlrev_b64 v[120:121], 12, v[170:171]
	v_add_f32_e32 v123, 1.0, v123
	v_rcp_f32_e32 v123, v123
	s_nop 0
	v_mul_f32_e32 v119, v119, v123
	v_cvt_pk_bf16_f32 v119, v122, v119
	global_store_dwordx4 v[124:125], v[116:119], off offset:256
	s_nop 1
	v_mov_b64_e32 v[116:117], s[34:35]
	v_mad_i64_i32 v[118:119], s[0:1], v170, s40, v[116:117]
	v_lshl_add_u64 v[122:123], v[118:119], 0, v[98:99]
	v_lshl_add_u64 v[118:119], v[122:123], 0, s[8:9]
	v_add_co_u32_e32 v122, vcc, s62, v122
	s_nop 1
	v_addc_co_u32_e32 v123, vcc, 0, v123, vcc
	s_nop 1
	s_waitcnt vmcnt(7)
	v_mov_b32_e32 v122, v208
	v_mov_b32_e32 v123, v209
	v_mov_b32_e32 v124, v210
	v_mov_b32_e32 v125, v211
	s_mov_b32 s98, 0x1fe000
	s_mov_b32 s99, 0
	v_lshl_add_u64 v[248:249], v[248:249], 0, s[98:99]
	global_load_dwordx4 v[208:211], v[248:249], off
	v_lshlrev_b32_e32 v96, 16, v122
	v_mul_f32_e32 v96, 0xbfb8aa3b, v96
	v_exp_f32_e32 v96, v96
	s_nop 0
	v_add_f32_e32 v96, 1.0, v96
	v_rcp_f32_e32 v96, v96
	s_nop 0
	v_mul_f32_e32 v96, v112, v96
	v_lshlrev_b32_e32 v112, 16, v124
	v_mul_f32_e32 v112, 0xbfb8aa3b, v112
	v_exp_f32_e32 v112, v112
	s_nop 0
	v_add_f32_e32 v112, 1.0, v112
	v_rcp_f32_e32 v112, v112
	s_nop 0
	v_mul_f32_e32 v112, v108, v112
	v_and_b32_e32 v108, 0xffff0000, v122
	v_mul_f32_e32 v108, 0xbfb8aa3b, v108
	v_exp_f32_e32 v108, v108
	s_nop 0
	v_add_f32_e32 v108, 1.0, v108
	v_rcp_f32_e32 v108, v108
	s_nop 0
	v_mul_f32_e32 v113, v113, v108
	v_and_b32_e32 v108, 0xffff0000, v124
	v_mul_f32_e32 v108, 0xbfb8aa3b, v108
	v_exp_f32_e32 v108, v108
	s_nop 0
	v_add_f32_e32 v108, 1.0, v108
	v_rcp_f32_e32 v108, v108
	s_nop 0
	v_mul_f32_e32 v122, v109, v108
	v_lshlrev_b32_e32 v108, 16, v123
	v_mul_f32_e32 v108, 0xbfb8aa3b, v108
	v_exp_f32_e32 v108, v108
	s_nop 0
	v_add_f32_e32 v108, 1.0, v108
	v_rcp_f32_e32 v108, v108
	s_nop 0
	v_mul_f32_e32 v114, v114, v108
	v_lshlrev_b32_e32 v108, 16, v125
	v_mul_f32_e32 v108, 0xbfb8aa3b, v108
	v_exp_f32_e32 v108, v108
	s_nop 0
	v_add_f32_e32 v108, 1.0, v108
	v_rcp_f32_e32 v108, v108
	s_nop 0
	v_mul_f32_e32 v124, v110, v108
	v_and_b32_e32 v108, 0xffff0000, v123
	v_mul_f32_e32 v108, 0xbfb8aa3b, v108
	v_exp_f32_e32 v108, v108
	v_cvt_pk_bf16_f32 v110, v96, v113
	s_nop 0
	v_add_f32_e32 v108, 1.0, v108
	v_rcp_f32_e32 v108, v108
	s_nop 0
	v_mul_f32_e32 v115, v115, v108
	v_and_b32_e32 v108, 0xffff0000, v125
	v_mul_f32_e32 v108, 0xbfb8aa3b, v108
	v_exp_f32_e32 v108, v108
	s_nop 0
	v_add_f32_e32 v108, 1.0, v108
	v_rcp_f32_e32 v108, v108
	s_nop 0
	v_mul_f32_e32 v123, v111, v108
	v_lshl_add_u64 v[108:109], s[48:49], 0, v[120:121]
	v_lshl_add_u64 v[108:109], v[108:109], 0, v[98:99]
	v_cvt_pk_bf16_f32 v111, v114, v115
	v_cvt_pk_bf16_f32 v112, v112, v122
	v_cvt_pk_bf16_f32 v113, v124, v123
	global_store_dwordx4 v[108:109], v[110:113], off
	s_nop 1
	s_waitcnt vmcnt(8)
	v_mov_b32_e32 v110, v212
	v_mov_b32_e32 v111, v213
	v_mov_b32_e32 v112, v214
	v_mov_b32_e32 v113, v215
	global_load_dwordx4 v[212:215], v[248:249], off offset:256
	v_lshlrev_b32_e32 v96, 16, v110
	v_mul_f32_e32 v96, 0xbfb8aa3b, v96
	v_exp_f32_e32 v96, v96
	s_nop 0
	v_add_f32_e32 v96, 1.0, v96
	v_rcp_f32_e32 v96, v96
	s_nop 0
	v_mul_f32_e32 v96, v104, v96
	v_lshlrev_b32_e32 v104, 16, v112
	v_mul_f32_e32 v104, 0xbfb8aa3b, v104
	v_exp_f32_e32 v104, v104
	s_nop 0
	v_add_f32_e32 v104, 1.0, v104
	v_rcp_f32_e32 v104, v104
	s_nop 0
	v_mul_f32_e32 v104, v100, v104
	v_and_b32_e32 v100, 0xffff0000, v110
	v_mul_f32_e32 v100, 0xbfb8aa3b, v100
	v_exp_f32_e32 v100, v100
	s_nop 0
	v_add_f32_e32 v100, 1.0, v100
	v_rcp_f32_e32 v100, v100
	s_nop 0
	v_mul_f32_e32 v100, v105, v100
	v_and_b32_e32 v105, 0xffff0000, v112
	v_mul_f32_e32 v105, 0xbfb8aa3b, v105
	v_exp_f32_e32 v105, v105
	v_cvt_pk_bf16_f32 v100, v96, v100
	s_nop 0
	v_add_f32_e32 v105, 1.0, v105
	v_rcp_f32_e32 v105, v105
	s_nop 0
	v_mul_f32_e32 v105, v101, v105
	v_lshlrev_b32_e32 v101, 16, v111
	v_mul_f32_e32 v101, 0xbfb8aa3b, v101
	v_exp_f32_e32 v101, v101
	s_nop 0
	v_add_f32_e32 v101, 1.0, v101
	v_rcp_f32_e32 v101, v101
	s_nop 0
	v_mul_f32_e32 v101, v106, v101
	v_lshlrev_b32_e32 v106, 16, v113
	v_mul_f32_e32 v106, 0xbfb8aa3b, v106
	v_exp_f32_e32 v106, v106
	s_nop 0
	v_add_f32_e32 v106, 1.0, v106
	v_rcp_f32_e32 v106, v106
	s_nop 0
	v_mul_f32_e32 v106, v102, v106
	v_and_b32_e32 v102, 0xffff0000, v111
	v_mul_f32_e32 v102, 0xbfb8aa3b, v102
	v_exp_f32_e32 v102, v102
	s_nop 0
	v_add_f32_e32 v102, 1.0, v102
	v_rcp_f32_e32 v102, v102
	s_nop 0
	v_mul_f32_e32 v102, v107, v102
	v_and_b32_e32 v107, 0xffff0000, v113
	v_mul_f32_e32 v107, 0xbfb8aa3b, v107
	v_exp_f32_e32 v107, v107
	v_cvt_pk_bf16_f32 v101, v101, v102
	v_cvt_pk_bf16_f32 v102, v104, v105
	s_nop 0
	v_add_f32_e32 v107, 1.0, v107
	v_rcp_f32_e32 v107, v107
	s_nop 0
	v_mul_f32_e32 v103, v103, v107
	v_cvt_pk_bf16_f32 v103, v106, v103
	global_store_dwordx4 v[108:109], v[100:103], off offset:256
	s_nop 1
	v_mad_i64_i32 v[100:101], s[0:1], v168, s40, v[116:117]
	v_lshl_add_u64 v[104:105], v[100:101], 0, v[98:99]
	v_lshl_add_u64 v[100:101], v[104:105], 0, s[8:9]
	v_add_co_u32_e32 v104, vcc, s62, v104
	v_lshlrev_b64 v[102:103], 12, v[168:169]
	s_nop 0
	v_addc_co_u32_e32 v105, vcc, 0, v105, vcc
	s_nop 1
	s_waitcnt vmcnt(9)
	v_mov_b32_e32 v104, v216
	v_mov_b32_e32 v105, v217
	v_mov_b32_e32 v106, v218
	v_mov_b32_e32 v107, v219
	s_mov_b32 s98, 0x66000
	s_mov_b32 s99, 0
	v_lshl_add_u64 v[248:249], v[248:249], 0, s[98:99]
	global_load_dwordx4 v[216:219], v[248:249], off
	v_lshlrev_b32_e32 v96, 16, v104
	v_mul_f32_e32 v96, 0xbfb8aa3b, v96
	v_exp_f32_e32 v96, v96
	s_nop 0
	v_add_f32_e32 v96, 1.0, v96
	v_rcp_f32_e32 v96, v96
	s_nop 0
	v_mul_f32_e32 v92, v92, v96
	v_lshlrev_b32_e32 v96, 16, v106
	v_mul_f32_e32 v96, 0xbfb8aa3b, v96
	v_exp_f32_e32 v96, v96
	s_nop 0
	v_add_f32_e32 v96, 1.0, v96
	v_rcp_f32_e32 v96, v96
	s_nop 0
	v_mul_f32_e32 v96, v88, v96
	v_and_b32_e32 v88, 0xffff0000, v104
	v_mul_f32_e32 v88, 0xbfb8aa3b, v88
	v_exp_f32_e32 v88, v88
	s_nop 0
	v_add_f32_e32 v88, 1.0, v88
	v_rcp_f32_e32 v88, v88
	s_nop 0
	v_mul_f32_e32 v93, v93, v88
	v_and_b32_e32 v88, 0xffff0000, v106
	v_mul_f32_e32 v88, 0xbfb8aa3b, v88
	v_exp_f32_e32 v88, v88
	s_nop 0
	v_add_f32_e32 v88, 1.0, v88
	v_rcp_f32_e32 v88, v88
	s_nop 0
	v_mul_f32_e32 v104, v89, v88
	v_lshlrev_b32_e32 v88, 16, v105
	v_mul_f32_e32 v88, 0xbfb8aa3b, v88
	v_exp_f32_e32 v88, v88
	s_nop 0
	v_add_f32_e32 v88, 1.0, v88
	v_rcp_f32_e32 v88, v88
	s_nop 0
	v_mul_f32_e32 v94, v94, v88
	v_lshlrev_b32_e32 v88, 16, v107
	v_mul_f32_e32 v88, 0xbfb8aa3b, v88
	v_exp_f32_e32 v88, v88
	s_nop 0
	v_add_f32_e32 v88, 1.0, v88
	v_rcp_f32_e32 v88, v88
	s_nop 0
	v_mul_f32_e32 v106, v90, v88
	v_and_b32_e32 v88, 0xffff0000, v105
	v_mul_f32_e32 v88, 0xbfb8aa3b, v88
	v_exp_f32_e32 v88, v88
	v_cvt_pk_bf16_f32 v90, v92, v93
	s_nop 0
	v_add_f32_e32 v88, 1.0, v88
	v_rcp_f32_e32 v88, v88
	s_nop 0
	v_mul_f32_e32 v95, v95, v88
	v_and_b32_e32 v88, 0xffff0000, v107
	v_mul_f32_e32 v88, 0xbfb8aa3b, v88
	v_exp_f32_e32 v88, v88
	s_nop 0
	v_add_f32_e32 v88, 1.0, v88
	v_rcp_f32_e32 v88, v88
	s_nop 0
	v_mul_f32_e32 v105, v91, v88
	v_lshl_add_u64 v[88:89], s[48:49], 0, v[102:103]
	v_lshl_add_u64 v[88:89], v[88:89], 0, v[98:99]
	v_cvt_pk_bf16_f32 v91, v94, v95
	v_cvt_pk_bf16_f32 v92, v96, v104
	v_cvt_pk_bf16_f32 v93, v106, v105
	global_store_dwordx4 v[88:89], v[90:93], off
	s_nop 1
	s_waitcnt vmcnt(10)
	v_mov_b32_e32 v90, v220
	v_mov_b32_e32 v91, v221
	v_mov_b32_e32 v92, v222
	v_mov_b32_e32 v93, v223
	global_load_dwordx4 v[220:223], v[248:249], off offset:256
	v_lshlrev_b32_e32 v94, 16, v90
	v_mul_f32_e32 v94, 0xbfb8aa3b, v94
	v_exp_f32_e32 v94, v94
	s_nop 0
	v_add_f32_e32 v94, 1.0, v94
	v_rcp_f32_e32 v94, v94
	s_nop 0
	v_mul_f32_e32 v84, v84, v94
	v_lshlrev_b32_e32 v94, 16, v92
	v_mul_f32_e32 v94, 0xbfb8aa3b, v94
	v_exp_f32_e32 v94, v94
	s_nop 0
	v_add_f32_e32 v94, 1.0, v94
	v_rcp_f32_e32 v94, v94
	s_nop 0
	v_mul_f32_e32 v94, v80, v94
	v_and_b32_e32 v80, 0xffff0000, v90
	v_mul_f32_e32 v80, 0xbfb8aa3b, v80
	v_exp_f32_e32 v80, v80
	s_nop 0
	v_add_f32_e32 v80, 1.0, v80
	v_rcp_f32_e32 v80, v80
	s_nop 0
	v_mul_f32_e32 v80, v85, v80
	v_and_b32_e32 v85, 0xffff0000, v92
	v_mul_f32_e32 v85, 0xbfb8aa3b, v85
	v_exp_f32_e32 v85, v85
	v_cvt_pk_bf16_f32 v80, v84, v80
	s_nop 0
	v_add_f32_e32 v85, 1.0, v85
	v_rcp_f32_e32 v85, v85
	s_nop 0
	v_mul_f32_e32 v85, v81, v85
	v_lshlrev_b32_e32 v81, 16, v91
	v_mul_f32_e32 v81, 0xbfb8aa3b, v81
	v_exp_f32_e32 v81, v81
	s_nop 0
	v_add_f32_e32 v81, 1.0, v81
	v_rcp_f32_e32 v81, v81
	s_nop 0
	v_mul_f32_e32 v81, v86, v81
	v_lshlrev_b32_e32 v86, 16, v93
	v_mul_f32_e32 v86, 0xbfb8aa3b, v86
	v_exp_f32_e32 v86, v86
	s_nop 0
	v_add_f32_e32 v86, 1.0, v86
	v_rcp_f32_e32 v86, v86
	s_nop 0
	v_mul_f32_e32 v86, v82, v86
	v_and_b32_e32 v82, 0xffff0000, v91
	v_mul_f32_e32 v82, 0xbfb8aa3b, v82
	v_exp_f32_e32 v82, v82
	s_nop 0
	v_add_f32_e32 v82, 1.0, v82
	v_rcp_f32_e32 v82, v82
	s_nop 0
	v_mul_f32_e32 v82, v87, v82
	v_and_b32_e32 v87, 0xffff0000, v93
	v_mul_f32_e32 v87, 0xbfb8aa3b, v87
	v_exp_f32_e32 v87, v87
	v_cvt_pk_bf16_f32 v81, v81, v82
	v_cvt_pk_bf16_f32 v82, v94, v85
	s_nop 0
	v_add_f32_e32 v87, 1.0, v87
	v_rcp_f32_e32 v87, v87
	s_nop 0
	v_mul_f32_e32 v83, v83, v87
	v_cvt_pk_bf16_f32 v83, v86, v83
	global_store_dwordx4 v[88:89], v[80:83], off offset:256
	s_nop 1
	v_mad_i64_i32 v[80:81], s[0:1], v156, s40, v[116:117]
	v_lshl_add_u64 v[84:85], v[80:81], 0, v[98:99]
	v_lshl_add_u64 v[80:81], v[84:85], 0, s[8:9]
	v_add_co_u32_e32 v84, vcc, s62, v84
	v_lshlrev_b64 v[82:83], 12, v[156:157]
	s_nop 0
	v_addc_co_u32_e32 v85, vcc, 0, v85, vcc
	s_nop 1
	s_waitcnt vmcnt(11)
	v_mov_b32_e32 v84, v200
	v_mov_b32_e32 v85, v201
	v_mov_b32_e32 v86, v202
	v_mov_b32_e32 v87, v203
	s_mov_b32 s98, 0x66000
	s_mov_b32 s99, 0
	v_lshl_add_u64 v[248:249], v[248:249], 0, s[98:99]
	global_load_dwordx4 v[200:203], v[248:249], off
	v_lshlrev_b32_e32 v88, 16, v84
	v_mul_f32_e32 v88, 0xbfb8aa3b, v88
	v_exp_f32_e32 v88, v88
	s_nop 0
	v_add_f32_e32 v88, 1.0, v88
	v_rcp_f32_e32 v88, v88
	s_nop 0
	v_mul_f32_e32 v76, v76, v88
	v_lshlrev_b32_e32 v88, 16, v86
	v_mul_f32_e32 v88, 0xbfb8aa3b, v88
	v_exp_f32_e32 v88, v88
	s_nop 0
	v_add_f32_e32 v88, 1.0, v88
	v_rcp_f32_e32 v88, v88
	s_nop 0
	v_mul_f32_e32 v88, v72, v88
	v_and_b32_e32 v72, 0xffff0000, v84
	v_mul_f32_e32 v72, 0xbfb8aa3b, v72
	v_exp_f32_e32 v72, v72
	s_nop 0
	v_add_f32_e32 v72, 1.0, v72
	v_rcp_f32_e32 v72, v72
	s_nop 0
	v_mul_f32_e32 v77, v77, v72
	v_and_b32_e32 v72, 0xffff0000, v86
	v_mul_f32_e32 v72, 0xbfb8aa3b, v72
	v_exp_f32_e32 v72, v72
	s_nop 0
	v_add_f32_e32 v72, 1.0, v72
	v_rcp_f32_e32 v72, v72
	s_nop 0
	v_mul_f32_e32 v84, v73, v72
	v_lshlrev_b32_e32 v72, 16, v85
	v_mul_f32_e32 v72, 0xbfb8aa3b, v72
	v_exp_f32_e32 v72, v72
	s_nop 0
	v_add_f32_e32 v72, 1.0, v72
	v_rcp_f32_e32 v72, v72
	s_nop 0
	v_mul_f32_e32 v78, v78, v72
	v_lshlrev_b32_e32 v72, 16, v87
	v_mul_f32_e32 v72, 0xbfb8aa3b, v72
	v_exp_f32_e32 v72, v72
	s_nop 0
	v_add_f32_e32 v72, 1.0, v72
	v_rcp_f32_e32 v72, v72
	s_nop 0
	v_mul_f32_e32 v86, v74, v72
	v_and_b32_e32 v72, 0xffff0000, v85
	v_mul_f32_e32 v72, 0xbfb8aa3b, v72
	v_exp_f32_e32 v72, v72
	v_cvt_pk_bf16_f32 v74, v76, v77
	s_nop 0
	v_add_f32_e32 v72, 1.0, v72
	v_rcp_f32_e32 v72, v72
	s_nop 0
	v_mul_f32_e32 v79, v79, v72
	v_and_b32_e32 v72, 0xffff0000, v87
	v_mul_f32_e32 v72, 0xbfb8aa3b, v72
	v_exp_f32_e32 v72, v72
	s_nop 0
	v_add_f32_e32 v72, 1.0, v72
	v_rcp_f32_e32 v72, v72
	s_nop 0
	v_mul_f32_e32 v85, v75, v72
	v_lshl_add_u64 v[72:73], s[48:49], 0, v[82:83]
	v_lshl_add_u64 v[72:73], v[72:73], 0, v[98:99]
	v_cvt_pk_bf16_f32 v75, v78, v79
	v_cvt_pk_bf16_f32 v76, v88, v84
	v_cvt_pk_bf16_f32 v77, v86, v85
	global_store_dwordx4 v[72:73], v[74:77], off
	s_nop 1
	s_waitcnt vmcnt(11)
	v_mov_b32_e32 v74, v204
	v_mov_b32_e32 v75, v205
	v_mov_b32_e32 v76, v206
	v_mov_b32_e32 v77, v207
	global_load_dwordx4 v[204:207], v[248:249], off offset:256
	v_lshlrev_b32_e32 v78, 16, v74
	v_mul_f32_e32 v78, 0xbfb8aa3b, v78
	v_exp_f32_e32 v78, v78
	s_nop 0
	v_add_f32_e32 v78, 1.0, v78
	v_rcp_f32_e32 v78, v78
	s_nop 0
	v_mul_f32_e32 v68, v68, v78
	v_lshlrev_b32_e32 v78, 16, v76
	v_mul_f32_e32 v78, 0xbfb8aa3b, v78
	v_exp_f32_e32 v78, v78
	s_nop 0
	v_add_f32_e32 v78, 1.0, v78
	v_rcp_f32_e32 v78, v78
	s_nop 0
	v_mul_f32_e32 v78, v64, v78
	v_and_b32_e32 v64, 0xffff0000, v74
	v_mul_f32_e32 v64, 0xbfb8aa3b, v64
	v_exp_f32_e32 v64, v64
	s_nop 0
	v_add_f32_e32 v64, 1.0, v64
	v_rcp_f32_e32 v64, v64
	s_nop 0
	v_mul_f32_e32 v64, v69, v64
	v_and_b32_e32 v69, 0xffff0000, v76
	v_mul_f32_e32 v69, 0xbfb8aa3b, v69
	v_exp_f32_e32 v69, v69
	v_cvt_pk_bf16_f32 v64, v68, v64
	s_nop 0
	v_add_f32_e32 v69, 1.0, v69
	v_rcp_f32_e32 v69, v69
	s_nop 0
	v_mul_f32_e32 v69, v65, v69
	v_lshlrev_b32_e32 v65, 16, v75
	v_mul_f32_e32 v65, 0xbfb8aa3b, v65
	v_exp_f32_e32 v65, v65
	s_nop 0
	v_add_f32_e32 v65, 1.0, v65
	v_rcp_f32_e32 v65, v65
	s_nop 0
	v_mul_f32_e32 v65, v70, v65
	v_lshlrev_b32_e32 v70, 16, v77
	v_mul_f32_e32 v70, 0xbfb8aa3b, v70
	v_exp_f32_e32 v70, v70
	s_nop 0
	v_add_f32_e32 v70, 1.0, v70
	v_rcp_f32_e32 v70, v70
	s_nop 0
	v_mul_f32_e32 v70, v66, v70
	v_and_b32_e32 v66, 0xffff0000, v75
	v_mul_f32_e32 v66, 0xbfb8aa3b, v66
	v_exp_f32_e32 v66, v66
	s_nop 0
	v_add_f32_e32 v66, 1.0, v66
	v_rcp_f32_e32 v66, v66
	s_nop 0
	v_mul_f32_e32 v66, v71, v66
	v_and_b32_e32 v71, 0xffff0000, v77
	v_mul_f32_e32 v71, 0xbfb8aa3b, v71
	v_exp_f32_e32 v71, v71
	v_cvt_pk_bf16_f32 v65, v65, v66
	v_cvt_pk_bf16_f32 v66, v78, v69
	s_nop 0
	v_add_f32_e32 v71, 1.0, v71
	v_rcp_f32_e32 v71, v71
	s_nop 0
	v_mul_f32_e32 v67, v67, v71
	v_cvt_pk_bf16_f32 v67, v70, v67
	global_store_dwordx4 v[72:73], v[64:67], off offset:256
	s_nop 1
	v_mad_i64_i32 v[64:65], s[0:1], v154, s40, v[116:117]
	v_lshl_add_u64 v[68:69], v[64:65], 0, v[98:99]
	v_lshl_add_u64 v[64:65], v[68:69], 0, s[8:9]
	v_add_co_u32_e32 v68, vcc, s62, v68
	v_lshlrev_b64 v[66:67], 12, v[154:155]
	s_nop 0
	v_addc_co_u32_e32 v69, vcc, 0, v69, vcc
	s_nop 1
	s_waitcnt vmcnt(11)
	v_mov_b32_e32 v68, v208
	v_mov_b32_e32 v69, v209
	v_mov_b32_e32 v70, v210
	v_mov_b32_e32 v71, v211
	s_mov_b32 s98, 0x66000
	s_mov_b32 s99, 0
	v_lshl_add_u64 v[248:249], v[248:249], 0, s[98:99]
	global_load_dwordx4 v[208:211], v[248:249], off
	v_lshlrev_b32_e32 v72, 16, v68
	v_mul_f32_e32 v72, 0xbfb8aa3b, v72
	v_exp_f32_e32 v72, v72
	s_nop 0
	v_add_f32_e32 v72, 1.0, v72
	v_rcp_f32_e32 v72, v72
	s_nop 0
	v_mul_f32_e32 v60, v60, v72
	v_lshlrev_b32_e32 v72, 16, v70
	v_mul_f32_e32 v72, 0xbfb8aa3b, v72
	v_exp_f32_e32 v72, v72
	s_nop 0
	v_add_f32_e32 v72, 1.0, v72
	v_rcp_f32_e32 v72, v72
	s_nop 0
	v_mul_f32_e32 v72, v56, v72
	v_and_b32_e32 v56, 0xffff0000, v68
	v_mul_f32_e32 v56, 0xbfb8aa3b, v56
	v_exp_f32_e32 v56, v56
	s_nop 0
	v_add_f32_e32 v56, 1.0, v56
	v_rcp_f32_e32 v56, v56
	s_nop 0
	v_mul_f32_e32 v61, v61, v56
	v_and_b32_e32 v56, 0xffff0000, v70
	v_mul_f32_e32 v56, 0xbfb8aa3b, v56
	v_exp_f32_e32 v56, v56
	s_nop 0
	v_add_f32_e32 v56, 1.0, v56
	v_rcp_f32_e32 v56, v56
	s_nop 0
	v_mul_f32_e32 v68, v57, v56
	v_lshlrev_b32_e32 v56, 16, v69
	v_mul_f32_e32 v56, 0xbfb8aa3b, v56
	v_exp_f32_e32 v56, v56
	s_nop 0
	v_add_f32_e32 v56, 1.0, v56
	v_rcp_f32_e32 v56, v56
	s_nop 0
	v_mul_f32_e32 v62, v62, v56
	v_lshlrev_b32_e32 v56, 16, v71
	v_mul_f32_e32 v56, 0xbfb8aa3b, v56
	v_exp_f32_e32 v56, v56
	s_nop 0
	v_add_f32_e32 v56, 1.0, v56
	v_rcp_f32_e32 v56, v56
	s_nop 0
	v_mul_f32_e32 v70, v58, v56
	v_and_b32_e32 v56, 0xffff0000, v69
	v_mul_f32_e32 v56, 0xbfb8aa3b, v56
	v_exp_f32_e32 v56, v56
	v_cvt_pk_bf16_f32 v58, v60, v61
	s_nop 0
	v_add_f32_e32 v56, 1.0, v56
	v_rcp_f32_e32 v56, v56
	s_nop 0
	v_mul_f32_e32 v63, v63, v56
	v_and_b32_e32 v56, 0xffff0000, v71
	v_mul_f32_e32 v56, 0xbfb8aa3b, v56
	v_exp_f32_e32 v56, v56
	s_nop 0
	v_add_f32_e32 v56, 1.0, v56
	v_rcp_f32_e32 v56, v56
	s_nop 0
	v_mul_f32_e32 v69, v59, v56
	v_lshl_add_u64 v[56:57], s[48:49], 0, v[66:67]
	v_lshl_add_u64 v[56:57], v[56:57], 0, v[98:99]
	v_cvt_pk_bf16_f32 v59, v62, v63
	v_cvt_pk_bf16_f32 v60, v72, v68
	v_cvt_pk_bf16_f32 v61, v70, v69
	global_store_dwordx4 v[56:57], v[58:61], off
	s_nop 1
	s_waitcnt vmcnt(11)
	v_mov_b32_e32 v58, v212
	v_mov_b32_e32 v59, v213
	v_mov_b32_e32 v60, v214
	v_mov_b32_e32 v61, v215
	global_load_dwordx4 v[212:215], v[248:249], off offset:256
	v_lshlrev_b32_e32 v62, 16, v58
	v_mul_f32_e32 v62, 0xbfb8aa3b, v62
	v_exp_f32_e32 v62, v62
	s_nop 0
	v_add_f32_e32 v62, 1.0, v62
	v_rcp_f32_e32 v62, v62
	s_nop 0
	v_mul_f32_e32 v52, v52, v62
	v_lshlrev_b32_e32 v62, 16, v60
	v_mul_f32_e32 v62, 0xbfb8aa3b, v62
	v_exp_f32_e32 v62, v62
	s_nop 0
	v_add_f32_e32 v62, 1.0, v62
	v_rcp_f32_e32 v62, v62
	s_nop 0
	v_mul_f32_e32 v62, v48, v62
	v_and_b32_e32 v48, 0xffff0000, v58
	v_mul_f32_e32 v48, 0xbfb8aa3b, v48
	v_exp_f32_e32 v48, v48
	s_nop 0
	v_add_f32_e32 v48, 1.0, v48
	v_rcp_f32_e32 v48, v48
	s_nop 0
	v_mul_f32_e32 v48, v53, v48
	v_and_b32_e32 v53, 0xffff0000, v60
	v_mul_f32_e32 v53, 0xbfb8aa3b, v53
	v_exp_f32_e32 v53, v53
	v_cvt_pk_bf16_f32 v48, v52, v48
	s_nop 0
	v_add_f32_e32 v53, 1.0, v53
	v_rcp_f32_e32 v53, v53
	s_nop 0
	v_mul_f32_e32 v53, v49, v53
	v_lshlrev_b32_e32 v49, 16, v59
	v_mul_f32_e32 v49, 0xbfb8aa3b, v49
	v_exp_f32_e32 v49, v49
	s_nop 0
	v_add_f32_e32 v49, 1.0, v49
	v_rcp_f32_e32 v49, v49
	s_nop 0
	v_mul_f32_e32 v49, v54, v49
	v_lshlrev_b32_e32 v54, 16, v61
	v_mul_f32_e32 v54, 0xbfb8aa3b, v54
	v_exp_f32_e32 v54, v54
	s_nop 0
	v_add_f32_e32 v54, 1.0, v54
	v_rcp_f32_e32 v54, v54
	s_nop 0
	v_mul_f32_e32 v54, v50, v54
	v_and_b32_e32 v50, 0xffff0000, v59
	v_mul_f32_e32 v50, 0xbfb8aa3b, v50
	v_exp_f32_e32 v50, v50
	s_nop 0
	v_add_f32_e32 v50, 1.0, v50
	v_rcp_f32_e32 v50, v50
	s_nop 0
	v_mul_f32_e32 v50, v55, v50
	v_and_b32_e32 v55, 0xffff0000, v61
	v_mul_f32_e32 v55, 0xbfb8aa3b, v55
	v_exp_f32_e32 v55, v55
	v_cvt_pk_bf16_f32 v49, v49, v50
	v_cvt_pk_bf16_f32 v50, v62, v53
	s_nop 0
	v_add_f32_e32 v55, 1.0, v55
	v_rcp_f32_e32 v55, v55
	s_nop 0
	v_mul_f32_e32 v51, v51, v55
	v_cvt_pk_bf16_f32 v51, v54, v51
	global_store_dwordx4 v[56:57], v[48:51], off offset:256
	s_nop 1
	v_mad_i64_i32 v[48:49], s[0:1], v152, s40, v[116:117]
	v_lshl_add_u64 v[52:53], v[48:49], 0, v[98:99]
	v_lshl_add_u64 v[48:49], v[52:53], 0, s[8:9]
	v_add_co_u32_e32 v52, vcc, s62, v52
	v_lshlrev_b64 v[50:51], 12, v[152:153]
	s_nop 0
	v_addc_co_u32_e32 v53, vcc, 0, v53, vcc
	s_nop 1
	s_waitcnt vmcnt(11)
	v_mov_b32_e32 v52, v216
	v_mov_b32_e32 v53, v217
	v_mov_b32_e32 v54, v218
	v_mov_b32_e32 v55, v219
	v_lshlrev_b32_e32 v56, 16, v52
	v_mul_f32_e32 v56, 0xbfb8aa3b, v56
	v_exp_f32_e32 v56, v56
	s_nop 0
	v_add_f32_e32 v56, 1.0, v56
	v_rcp_f32_e32 v56, v56
	s_nop 0
	v_mul_f32_e32 v44, v44, v56
	v_lshlrev_b32_e32 v56, 16, v54
	v_mul_f32_e32 v56, 0xbfb8aa3b, v56
	v_exp_f32_e32 v56, v56
	s_nop 0
	v_add_f32_e32 v56, 1.0, v56
	v_rcp_f32_e32 v56, v56
	s_nop 0
	v_mul_f32_e32 v56, v40, v56
	v_and_b32_e32 v40, 0xffff0000, v52
	v_mul_f32_e32 v40, 0xbfb8aa3b, v40
	v_exp_f32_e32 v40, v40
	s_nop 0
	v_add_f32_e32 v40, 1.0, v40
	v_rcp_f32_e32 v40, v40
	s_nop 0
	v_mul_f32_e32 v45, v45, v40
	v_and_b32_e32 v40, 0xffff0000, v54
	v_mul_f32_e32 v40, 0xbfb8aa3b, v40
	v_exp_f32_e32 v40, v40
	s_nop 0
	v_add_f32_e32 v40, 1.0, v40
	v_rcp_f32_e32 v40, v40
	s_nop 0
	v_mul_f32_e32 v52, v41, v40
	v_lshlrev_b32_e32 v40, 16, v53
	v_mul_f32_e32 v40, 0xbfb8aa3b, v40
	v_exp_f32_e32 v40, v40
	s_nop 0
	v_add_f32_e32 v40, 1.0, v40
	v_rcp_f32_e32 v40, v40
	s_nop 0
	v_mul_f32_e32 v46, v46, v40
	v_lshlrev_b32_e32 v40, 16, v55
	v_mul_f32_e32 v40, 0xbfb8aa3b, v40
	v_exp_f32_e32 v40, v40
	s_nop 0
	v_add_f32_e32 v40, 1.0, v40
	v_rcp_f32_e32 v40, v40
	s_nop 0
	v_mul_f32_e32 v54, v42, v40
	v_and_b32_e32 v40, 0xffff0000, v53
	v_mul_f32_e32 v40, 0xbfb8aa3b, v40
	v_exp_f32_e32 v40, v40
	v_cvt_pk_bf16_f32 v42, v44, v45
	s_nop 0
	v_add_f32_e32 v40, 1.0, v40
	v_rcp_f32_e32 v40, v40
	s_nop 0
	v_mul_f32_e32 v47, v47, v40
	v_and_b32_e32 v40, 0xffff0000, v55
	v_mul_f32_e32 v40, 0xbfb8aa3b, v40
	v_exp_f32_e32 v40, v40
	s_nop 0
	v_add_f32_e32 v40, 1.0, v40
	v_rcp_f32_e32 v40, v40
	s_nop 0
	v_mul_f32_e32 v53, v43, v40
	v_lshl_add_u64 v[40:41], s[48:49], 0, v[50:51]
	v_lshl_add_u64 v[40:41], v[40:41], 0, v[98:99]
	v_cvt_pk_bf16_f32 v43, v46, v47
	v_cvt_pk_bf16_f32 v44, v56, v52
	v_cvt_pk_bf16_f32 v45, v54, v53
	global_store_dwordx4 v[40:41], v[42:45], off
	s_nop 1
	s_waitcnt vmcnt(10)
	v_mov_b32_e32 v42, v220
	v_mov_b32_e32 v43, v221
	v_mov_b32_e32 v44, v222
	v_mov_b32_e32 v45, v223
	v_lshlrev_b32_e32 v46, 16, v42
	v_mul_f32_e32 v46, 0xbfb8aa3b, v46
	v_exp_f32_e32 v46, v46
	s_nop 0
	v_add_f32_e32 v46, 1.0, v46
	v_rcp_f32_e32 v46, v46
	s_nop 0
	v_mul_f32_e32 v36, v36, v46
	v_lshlrev_b32_e32 v46, 16, v44
	v_mul_f32_e32 v46, 0xbfb8aa3b, v46
	v_exp_f32_e32 v46, v46
	s_nop 0
	v_add_f32_e32 v46, 1.0, v46
	v_rcp_f32_e32 v46, v46
	s_nop 0
	v_mul_f32_e32 v46, v32, v46
	v_and_b32_e32 v32, 0xffff0000, v42
	v_mul_f32_e32 v32, 0xbfb8aa3b, v32
	v_exp_f32_e32 v32, v32
	s_nop 0
	v_add_f32_e32 v32, 1.0, v32
	v_rcp_f32_e32 v32, v32
	s_nop 0
	v_mul_f32_e32 v32, v37, v32
	v_and_b32_e32 v37, 0xffff0000, v44
	v_mul_f32_e32 v37, 0xbfb8aa3b, v37
	v_exp_f32_e32 v37, v37
	v_cvt_pk_bf16_f32 v32, v36, v32
	s_nop 0
	v_add_f32_e32 v37, 1.0, v37
	v_rcp_f32_e32 v37, v37
	s_nop 0
	v_mul_f32_e32 v37, v33, v37
	v_lshlrev_b32_e32 v33, 16, v43
	v_mul_f32_e32 v33, 0xbfb8aa3b, v33
	v_exp_f32_e32 v33, v33
	s_nop 0
	v_add_f32_e32 v33, 1.0, v33
	v_rcp_f32_e32 v33, v33
	s_nop 0
	v_mul_f32_e32 v33, v38, v33
	v_lshlrev_b32_e32 v38, 16, v45
	v_mul_f32_e32 v38, 0xbfb8aa3b, v38
	v_exp_f32_e32 v38, v38
	s_nop 0
	v_add_f32_e32 v38, 1.0, v38
	v_rcp_f32_e32 v38, v38
	s_nop 0
	v_mul_f32_e32 v38, v34, v38
	v_and_b32_e32 v34, 0xffff0000, v43
	v_mul_f32_e32 v34, 0xbfb8aa3b, v34
	v_exp_f32_e32 v34, v34
	s_nop 0
	v_add_f32_e32 v34, 1.0, v34
	v_rcp_f32_e32 v34, v34
	s_nop 0
	v_mul_f32_e32 v34, v39, v34
	v_and_b32_e32 v39, 0xffff0000, v45
	v_mul_f32_e32 v39, 0xbfb8aa3b, v39
	v_exp_f32_e32 v39, v39
	v_cvt_pk_bf16_f32 v33, v33, v34
	v_cvt_pk_bf16_f32 v34, v46, v37
	s_nop 0
	v_add_f32_e32 v39, 1.0, v39
	v_rcp_f32_e32 v39, v39
	s_nop 0
	v_mul_f32_e32 v35, v35, v39
	v_cvt_pk_bf16_f32 v35, v38, v35
	global_store_dwordx4 v[40:41], v[32:35], off offset:256
	s_nop 1
	v_mad_i64_i32 v[32:33], s[0:1], v150, s40, v[116:117]
	v_lshl_add_u64 v[36:37], v[32:33], 0, v[98:99]
	v_lshl_add_u64 v[32:33], v[36:37], 0, s[8:9]
	v_add_co_u32_e32 v36, vcc, s62, v36
	v_lshlrev_b64 v[34:35], 12, v[150:151]
	s_nop 0
	v_addc_co_u32_e32 v37, vcc, 0, v37, vcc
	s_nop 1
	s_waitcnt vmcnt(9)
	v_mov_b32_e32 v36, v200
	v_mov_b32_e32 v37, v201
	v_mov_b32_e32 v38, v202
	v_mov_b32_e32 v39, v203
	v_lshlrev_b32_e32 v40, 16, v36
	v_mul_f32_e32 v40, 0xbfb8aa3b, v40
	v_exp_f32_e32 v40, v40
	s_nop 0
	v_add_f32_e32 v40, 1.0, v40
	v_rcp_f32_e32 v40, v40
	s_nop 0
	v_mul_f32_e32 v28, v28, v40
	v_lshlrev_b32_e32 v40, 16, v38
	v_mul_f32_e32 v40, 0xbfb8aa3b, v40
	v_exp_f32_e32 v40, v40
	s_nop 0
	v_add_f32_e32 v40, 1.0, v40
	v_rcp_f32_e32 v40, v40
	s_nop 0
	v_mul_f32_e32 v40, v24, v40
	v_and_b32_e32 v24, 0xffff0000, v36
	v_mul_f32_e32 v24, 0xbfb8aa3b, v24
	v_exp_f32_e32 v24, v24
	s_nop 0
	v_add_f32_e32 v24, 1.0, v24
	v_rcp_f32_e32 v24, v24
	s_nop 0
	v_mul_f32_e32 v29, v29, v24
	v_and_b32_e32 v24, 0xffff0000, v38
	v_mul_f32_e32 v24, 0xbfb8aa3b, v24
	v_exp_f32_e32 v24, v24
	s_nop 0
	v_add_f32_e32 v24, 1.0, v24
	v_rcp_f32_e32 v24, v24
	s_nop 0
	v_mul_f32_e32 v36, v25, v24
	v_lshlrev_b32_e32 v24, 16, v37
	v_mul_f32_e32 v24, 0xbfb8aa3b, v24
	v_exp_f32_e32 v24, v24
	s_nop 0
	v_add_f32_e32 v24, 1.0, v24
	v_rcp_f32_e32 v24, v24
	s_nop 0
	v_mul_f32_e32 v30, v30, v24
	v_lshlrev_b32_e32 v24, 16, v39
	v_mul_f32_e32 v24, 0xbfb8aa3b, v24
	v_exp_f32_e32 v24, v24
	s_nop 0
	v_add_f32_e32 v24, 1.0, v24
	v_rcp_f32_e32 v24, v24
	s_nop 0
	v_mul_f32_e32 v38, v26, v24
	v_and_b32_e32 v24, 0xffff0000, v37
	v_mul_f32_e32 v24, 0xbfb8aa3b, v24
	v_exp_f32_e32 v24, v24
	v_cvt_pk_bf16_f32 v26, v28, v29
	s_nop 0
	v_add_f32_e32 v24, 1.0, v24
	v_rcp_f32_e32 v24, v24
	s_nop 0
	v_mul_f32_e32 v31, v31, v24
	v_and_b32_e32 v24, 0xffff0000, v39
	v_mul_f32_e32 v24, 0xbfb8aa3b, v24
	v_exp_f32_e32 v24, v24
	s_nop 0
	v_add_f32_e32 v24, 1.0, v24
	v_rcp_f32_e32 v24, v24
	s_nop 0
	v_mul_f32_e32 v37, v27, v24
	v_lshl_add_u64 v[24:25], s[48:49], 0, v[34:35]
	v_lshl_add_u64 v[24:25], v[24:25], 0, v[98:99]
	v_cvt_pk_bf16_f32 v27, v30, v31
	v_cvt_pk_bf16_f32 v28, v40, v36
	v_cvt_pk_bf16_f32 v29, v38, v37
	global_store_dwordx4 v[24:25], v[26:29], off
	s_nop 1
	s_waitcnt vmcnt(8)
	v_mov_b32_e32 v26, v204
	v_mov_b32_e32 v27, v205
	v_mov_b32_e32 v28, v206
	v_mov_b32_e32 v29, v207
	v_lshlrev_b32_e32 v30, 16, v26
	v_mul_f32_e32 v30, 0xbfb8aa3b, v30
	v_exp_f32_e32 v30, v30
	s_nop 0
	v_add_f32_e32 v30, 1.0, v30
	v_rcp_f32_e32 v30, v30
	s_nop 0
	v_mul_f32_e32 v20, v20, v30
	v_lshlrev_b32_e32 v30, 16, v28
	v_mul_f32_e32 v30, 0xbfb8aa3b, v30
	v_exp_f32_e32 v30, v30
	s_nop 0
	v_add_f32_e32 v30, 1.0, v30
	v_rcp_f32_e32 v30, v30
	s_nop 0
	v_mul_f32_e32 v30, v16, v30
	v_and_b32_e32 v16, 0xffff0000, v26
	v_mul_f32_e32 v16, 0xbfb8aa3b, v16
	v_exp_f32_e32 v16, v16
	s_nop 0
	v_add_f32_e32 v16, 1.0, v16
	v_rcp_f32_e32 v16, v16
	s_nop 0
	v_mul_f32_e32 v16, v21, v16
	v_and_b32_e32 v21, 0xffff0000, v28
	v_mul_f32_e32 v21, 0xbfb8aa3b, v21
	v_exp_f32_e32 v21, v21
	v_cvt_pk_bf16_f32 v16, v20, v16
	s_nop 0
	v_add_f32_e32 v21, 1.0, v21
	v_rcp_f32_e32 v21, v21
	s_nop 0
	v_mul_f32_e32 v21, v17, v21
	v_lshlrev_b32_e32 v17, 16, v27
	v_mul_f32_e32 v17, 0xbfb8aa3b, v17
	v_exp_f32_e32 v17, v17
	s_nop 0
	v_add_f32_e32 v17, 1.0, v17
	v_rcp_f32_e32 v17, v17
	s_nop 0
	v_mul_f32_e32 v17, v22, v17
	v_lshlrev_b32_e32 v22, 16, v29
	v_mul_f32_e32 v22, 0xbfb8aa3b, v22
	v_exp_f32_e32 v22, v22
	s_nop 0
	v_add_f32_e32 v22, 1.0, v22
	v_rcp_f32_e32 v22, v22
	s_nop 0
	v_mul_f32_e32 v22, v18, v22
	v_and_b32_e32 v18, 0xffff0000, v27
	v_mul_f32_e32 v18, 0xbfb8aa3b, v18
	v_exp_f32_e32 v18, v18
	s_nop 0
	v_add_f32_e32 v18, 1.0, v18
	v_rcp_f32_e32 v18, v18
	s_nop 0
	v_mul_f32_e32 v18, v23, v18
	v_and_b32_e32 v23, 0xffff0000, v29
	v_mul_f32_e32 v23, 0xbfb8aa3b, v23
	v_exp_f32_e32 v23, v23
	v_cvt_pk_bf16_f32 v17, v17, v18
	v_cvt_pk_bf16_f32 v18, v30, v21
	s_nop 0
	v_add_f32_e32 v23, 1.0, v23
	v_rcp_f32_e32 v23, v23
	s_nop 0
	v_mul_f32_e32 v19, v19, v23
	v_cvt_pk_bf16_f32 v19, v22, v19
	global_store_dwordx4 v[24:25], v[16:19], off offset:256
	s_nop 1
	v_mad_i64_i32 v[16:17], s[0:1], v148, s40, v[116:117]
	v_lshl_add_u64 v[20:21], v[16:17], 0, v[98:99]
	v_lshl_add_u64 v[16:17], v[20:21], 0, s[8:9]
	v_add_co_u32_e32 v20, vcc, s62, v20
	v_lshlrev_b64 v[18:19], 12, v[148:149]
	s_nop 0
	v_addc_co_u32_e32 v21, vcc, 0, v21, vcc
	s_mov_b64 s[0:1], -1
	s_and_b64 vcc, exec, s[36:37]
	s_nop 1
	s_waitcnt vmcnt(7)
	v_mov_b32_e32 v20, v208
	v_mov_b32_e32 v21, v209
	v_mov_b32_e32 v22, v210
	v_mov_b32_e32 v23, v211
	v_lshlrev_b32_e32 v24, 16, v20
	v_mul_f32_e32 v24, 0xbfb8aa3b, v24
	v_exp_f32_e32 v24, v24
	s_nop 0
	v_add_f32_e32 v24, 1.0, v24
	v_rcp_f32_e32 v24, v24
	s_nop 0
	v_mul_f32_e32 v12, v12, v24
	v_lshlrev_b32_e32 v24, 16, v22
	v_mul_f32_e32 v24, 0xbfb8aa3b, v24
	v_exp_f32_e32 v24, v24
	s_nop 0
	v_add_f32_e32 v24, 1.0, v24
	v_rcp_f32_e32 v24, v24
	s_nop 0
	v_mul_f32_e32 v24, v8, v24
	v_and_b32_e32 v8, 0xffff0000, v20
	v_mul_f32_e32 v8, 0xbfb8aa3b, v8
	v_exp_f32_e32 v8, v8
	s_nop 0
	v_add_f32_e32 v8, 1.0, v8
	v_rcp_f32_e32 v8, v8
	s_nop 0
	v_mul_f32_e32 v13, v13, v8
	v_and_b32_e32 v8, 0xffff0000, v22
	v_mul_f32_e32 v8, 0xbfb8aa3b, v8
	v_exp_f32_e32 v8, v8
	s_nop 0
	v_add_f32_e32 v8, 1.0, v8
	v_rcp_f32_e32 v8, v8
	s_nop 0
	v_mul_f32_e32 v20, v9, v8
	v_lshlrev_b32_e32 v8, 16, v21
	v_mul_f32_e32 v8, 0xbfb8aa3b, v8
	v_exp_f32_e32 v8, v8
	s_nop 0
	v_add_f32_e32 v8, 1.0, v8
	v_rcp_f32_e32 v8, v8
	s_nop 0
	v_mul_f32_e32 v14, v14, v8
	v_lshlrev_b32_e32 v8, 16, v23
	v_mul_f32_e32 v8, 0xbfb8aa3b, v8
	v_exp_f32_e32 v8, v8
	s_nop 0
	v_add_f32_e32 v8, 1.0, v8
	v_rcp_f32_e32 v8, v8
	s_nop 0
	v_mul_f32_e32 v22, v10, v8
	v_and_b32_e32 v8, 0xffff0000, v21
	v_mul_f32_e32 v8, 0xbfb8aa3b, v8
	v_exp_f32_e32 v8, v8
	v_cvt_pk_bf16_f32 v10, v12, v13
	s_nop 0
	v_add_f32_e32 v8, 1.0, v8
	v_rcp_f32_e32 v8, v8
	s_nop 0
	v_mul_f32_e32 v15, v15, v8
	v_and_b32_e32 v8, 0xffff0000, v23
	v_mul_f32_e32 v8, 0xbfb8aa3b, v8
	v_exp_f32_e32 v8, v8
	s_nop 0
	v_add_f32_e32 v8, 1.0, v8
	v_rcp_f32_e32 v8, v8
	s_nop 0
	v_mul_f32_e32 v21, v11, v8
	v_lshl_add_u64 v[8:9], s[48:49], 0, v[18:19]
	v_lshl_add_u64 v[8:9], v[8:9], 0, v[98:99]
	v_cvt_pk_bf16_f32 v11, v14, v15
	v_cvt_pk_bf16_f32 v12, v24, v20
	v_cvt_pk_bf16_f32 v13, v22, v21
	global_store_dwordx4 v[8:9], v[10:13], off
	s_nop 1
	s_waitcnt vmcnt(6)
	v_mov_b32_e32 v10, v212
	v_mov_b32_e32 v11, v213
	v_mov_b32_e32 v12, v214
	v_mov_b32_e32 v13, v215
	v_lshlrev_b32_e32 v14, 16, v10
	v_mul_f32_e32 v14, 0xbfb8aa3b, v14
	v_exp_f32_e32 v14, v14
	s_nop 0
	v_add_f32_e32 v14, 1.0, v14
	v_rcp_f32_e32 v14, v14
	s_nop 0
	v_mul_f32_e32 v4, v4, v14
	v_lshlrev_b32_e32 v14, 16, v12
	v_mul_f32_e32 v14, 0xbfb8aa3b, v14
	v_exp_f32_e32 v14, v14
	s_nop 0
	v_add_f32_e32 v14, 1.0, v14
	v_rcp_f32_e32 v14, v14
	s_nop 0
	v_mul_f32_e32 v14, v0, v14
	v_and_b32_e32 v0, 0xffff0000, v10
	v_mul_f32_e32 v0, 0xbfb8aa3b, v0
	v_exp_f32_e32 v0, v0
	s_nop 0
	v_add_f32_e32 v0, 1.0, v0
	v_rcp_f32_e32 v0, v0
	s_nop 0
	v_mul_f32_e32 v0, v5, v0
	v_and_b32_e32 v5, 0xffff0000, v12
	v_mul_f32_e32 v5, 0xbfb8aa3b, v5
	v_exp_f32_e32 v5, v5
	v_cvt_pk_bf16_f32 v0, v4, v0
	s_nop 0
	v_add_f32_e32 v5, 1.0, v5
	v_rcp_f32_e32 v5, v5
	s_nop 0
	v_mul_f32_e32 v5, v1, v5
	v_lshlrev_b32_e32 v1, 16, v11
	v_mul_f32_e32 v1, 0xbfb8aa3b, v1
	v_exp_f32_e32 v1, v1
	s_nop 0
	v_add_f32_e32 v1, 1.0, v1
	v_rcp_f32_e32 v1, v1
	s_nop 0
	v_mul_f32_e32 v1, v6, v1
	v_lshlrev_b32_e32 v6, 16, v13
	v_mul_f32_e32 v6, 0xbfb8aa3b, v6
	v_exp_f32_e32 v6, v6
	s_nop 0
	v_add_f32_e32 v6, 1.0, v6
	v_rcp_f32_e32 v6, v6
	s_nop 0
	v_mul_f32_e32 v6, v2, v6
	v_and_b32_e32 v2, 0xffff0000, v11
	v_mul_f32_e32 v2, 0xbfb8aa3b, v2
	v_exp_f32_e32 v2, v2
	s_nop 0
	v_add_f32_e32 v2, 1.0, v2
	v_rcp_f32_e32 v2, v2
	s_nop 0
	v_mul_f32_e32 v2, v7, v2
	v_and_b32_e32 v7, 0xffff0000, v13
	v_mul_f32_e32 v7, 0xbfb8aa3b, v7
	v_exp_f32_e32 v7, v7
	v_cvt_pk_bf16_f32 v1, v1, v2
	v_cvt_pk_bf16_f32 v2, v14, v5
	s_nop 0
	v_add_f32_e32 v7, 1.0, v7
	v_rcp_f32_e32 v7, v7
	s_nop 0
	v_mul_f32_e32 v3, v3, v7
	v_cvt_pk_bf16_f32 v3, v6, v3
	global_store_dwordx4 v[8:9], v[0:3], off offset:256
	s_cbranch_vccnz .LBB0_947
	v_readlane_b32 s0, v255, 54
	v_readlane_b32 s1, v255, 55
	s_andn2_b64 vcc, exec, s[0:1]
	s_cbranch_vccnz .LBB0_946
	s_barrier
	s_branch .LBB0_946
